# attention: running reference enters the QK^T MFMA as SrcC (v[176:191] = -m) so the 32 v_sub per 64-key step go away; V tile b128 layout; LDS address registers relocated; f32 accumulate unchanged
# speedup vs baseline: 1.0174x; 1.0174x over previous
; DI float bflo(unsigned u) { return __uint_as_float(u << 16); }
; DI float bfhi(unsigned u) { return __uint_as_float(u & 0xffff0000u); }
; DI f32x16 zero16() { f32x16 z; for (int i = 0; i < 16; ++i) z[i] = 0.f; return z; }
; DI void phase_attn(const Params& p, int hf, bool skipctx, char* smem, int& rot) {
;     ...
;       uint4 qu[6];
; #pragma unroll
;       for (int ks = 0; ks < 6; ++ks) qu[ks] = *(const uint4*)(Qb + tq * 768 + head * 96 + ks * 16 + h * 8);
; #pragma unroll
;       for (int ks = 0; ks < 4; ++ks) {
;         const uint4 u = qu[ks];
;         qf[ks] = pack8(bflo(u.x) * QSCALE, bfhi(u.x) * QSCALE, bflo(u.y) * QSCALE, bfhi(u.y) * QSCALE, bflo(u.z) * QSCALE, bfhi(u.z) * QSCALE, bflo(u.w) * QSCALE, bfhi(u.w) * QSCALE);
;       }
;       const unsigned a1[4] = {qu[4].x, qu[4].y, qu[4].z, qu[4].w}, a2[4] = {qu[5].x, qu[5].y, qu[5].z, qu[5].w};
;       float o1[8], o2[8];
;       const int sq_ = s0 + w * 32 + r;
; #pragma unroll
;       for (int e = 0; e < 8; ++e) {
;         const float x1 = ((e & 1) ? bfhi(a1[e >> 1]) : bflo(a1[e >> 1])) * QSCALE;
;         const float x2 = ((e & 1) ? bfhi(a2[e >> 1]) : bflo(a2[e >> 1])) * QSCALE;
;         float cs = 1.f, sn = 0.f;
;         if (sq_ >= LC) { cs = axc[(sq_ - LC) * 16 + 8 * h + e]; sn = axs[(sq_ - LC) * 16 + 8 * h + e]; }
;         o1[e] = x1 * cs - x2 * sn; o2[e] = x1 * sn + x2 * cs;
;       }
;       qf[4] = pack8(o1[0], o1[1], o1[2], o1[3], o1[4], o1[5], o1[6], o1[7]);
;       qf[5] = pack8(o2[0], o2[1], o2[2], o2[3], o2[4], o2[5], o2[6], o2[7]);
;     }
;     const bf16_t* Kg = Kb + (size_t)(bl * 8 + head) * S * 96;
;     const bf16_t* Vg = VTb + (size_t)(bl * 8 + head) * 64 * S;
;     f32x16 o[2]; o[0] = zero16(); o[1] = zero16();
;     float m_run = -1e30f, l_run = 0.f;
;     uint4 ak0, ak1, ak2, av0, av1, bk0, bk1, bk2, bv0, bv1;
;     const int kr0 = tid / 12, kc0 = tid - kr0 * 12, kr1 = (tid + 512) / 12, kc1 = (tid + 512) - kr1 * 12, kr2 = (tid + 1024) / 12, kc2 = (tid + 1024) - kr2 * 12;
.LBB0_794:
	s_or_b64 exec, exec, s[26:27]
	s_waitcnt vmcnt(0)
	v_lshlrev_b32_e32 v27, 16, v23
	v_lshlrev_b32_e32 v26, 16, v19
	v_pk_mul_f32 v[26:27], v[26:27], s[48:49] op_sel_hi:[1,0]
	v_lshlrev_b32_e32 v47, 16, v22
	v_pk_mul_f32 v[28:29], v[26:27], v[30:31] op_sel:[0,1] op_sel_hi:[1,0]
	v_pk_mul_f32 v[26:27], v[26:27], v[30:31]
	v_and_b32_e32 v30, 0xffff0000, v19
	v_lshlrev_b32_e32 v46, 16, v18
	v_and_b32_e32 v19, 0xffff0000, v22
	v_and_b32_e32 v18, 0xffff0000, v18
	v_and_b32_e32 v31, 0xffff0000, v23
	v_pk_mul_f32 v[46:47], v[46:47], s[48:49] op_sel_hi:[1,0]
	v_pk_mul_f32 v[22:23], v[18:19], s[48:49] op_sel_hi:[1,0]
	v_pk_mul_f32 v[48:49], v[46:47], v[42:43] op_sel:[0,1] op_sel_hi:[1,0]
	v_pk_mul_f32 v[42:43], v[46:47], v[42:43]
	v_pk_mul_f32 v[18:19], v[22:23], v[40:41] op_sel:[0,1] op_sel_hi:[1,0]
	v_pk_mul_f32 v[22:23], v[22:23], v[40:41]
	v_mov_b32_e32 v40, v42
	v_mov_b32_e32 v41, v22
	v_mov_b32_e32 v22, v43
	v_pk_add_f32 v[22:23], v[40:41], v[22:23]
	v_lshlrev_b32_e32 v41, 16, v21
	v_lshlrev_b32_e32 v40, 16, v17
	v_pk_mul_f32 v[40:41], v[40:41], s[48:49] op_sel_hi:[1,0]
	v_mov_b32_e32 v46, v48
	v_mov_b32_e32 v47, v18
	v_mov_b32_e32 v18, v49
	v_pk_mul_f32 v[42:43], v[40:41], v[32:33] op_sel:[0,1] op_sel_hi:[1,0]
	v_pk_mul_f32 v[40:41], v[40:41], v[32:33]
	v_and_b32_e32 v33, 0xffff0000, v21
	v_and_b32_e32 v32, 0xffff0000, v17
	v_pk_add_f32 v[18:19], v[46:47], v[18:19] neg_lo:[0,1] neg_hi:[0,1]
	v_pk_mul_f32 v[46:47], v[32:33], s[48:49] op_sel_hi:[1,0]
	v_mov_b32_e32 v48, v42
	v_pk_mul_f32 v[32:33], v[46:47], v[34:35] op_sel:[0,1] op_sel_hi:[1,0]
	v_pk_mul_f32 v[34:35], v[46:47], v[34:35]
	v_mov_b32_e32 v49, v32
	v_mov_b32_e32 v32, v43
	v_mov_b32_e32 v42, v40
	v_mov_b32_e32 v43, v34
	v_mov_b32_e32 v34, v41
	v_lshlrev_b32_e32 v41, 16, v20
	v_lshlrev_b32_e32 v40, 16, v16
	v_and_b32_e32 v17, 0xffff0000, v20
	v_and_b32_e32 v16, 0xffff0000, v16
	v_pk_mul_f32 v[40:41], v[40:41], s[48:49] op_sel_hi:[1,0]
	v_pk_mul_f32 v[20:21], v[16:17], s[48:49] op_sel_hi:[1,0]
	v_pk_add_f32 v[34:35], v[42:43], v[34:35]
	v_pk_mul_f32 v[42:43], v[40:41], v[38:39] op_sel:[0,1] op_sel_hi:[1,0]
	v_pk_mul_f32 v[38:39], v[40:41], v[38:39]
	v_pk_mul_f32 v[16:17], v[20:21], v[36:37] op_sel:[0,1] op_sel_hi:[1,0]
	v_pk_mul_f32 v[20:21], v[20:21], v[36:37]
	v_mov_b32_e32 v36, v38
	v_mov_b32_e32 v37, v20
	v_mov_b32_e32 v20, v39
	v_pk_add_f32 v[20:21], v[36:37], v[20:21]
	v_lshlrev_b32_e32 v36, 16, v12
	v_and_b32_e32 v37, 0xffff0000, v12
	v_lshlrev_b32_e32 v12, 16, v13
	v_and_b32_e32 v13, 0xffff0000, v13
	v_pk_mul_f32 v[12:13], v[12:13], s[48:49] op_sel_hi:[1,0]
	v_lshlrev_b32_e32 v38, 16, v14
	v_cvt_pk_bf16_f32 v65, v12, v13
	v_lshlrev_b32_e32 v12, 16, v8
	v_and_b32_e32 v13, 0xffff0000, v8
	v_lshlrev_b32_e32 v8, 16, v9
	v_and_b32_e32 v9, 0xffff0000, v9
	v_pk_mul_f32 v[8:9], v[8:9], s[48:49] op_sel_hi:[1,0]
	v_and_b32_e32 v39, 0xffff0000, v14
	v_cvt_pk_bf16_f32 v69, v8, v9
	v_lshlrev_b32_e32 v8, 16, v4
	v_and_b32_e32 v9, 0xffff0000, v4
	v_lshlrev_b32_e32 v4, 16, v5
	v_and_b32_e32 v5, 0xffff0000, v5
	v_lshlrev_b32_e32 v14, 16, v15
	v_and_b32_e32 v15, 0xffff0000, v15
	v_pk_mul_f32 v[4:5], v[4:5], s[48:49] op_sel_hi:[1,0]
	s_mov_b32 s16, 0x2aaaaaab
	v_pk_mul_f32 v[14:15], v[14:15], s[48:49] op_sel_hi:[1,0]
	v_cvt_pk_bf16_f32 v73, v4, v5
	v_mul_hi_i32 v4, v160, s16
	v_cvt_pk_bf16_f32 v67, v14, v15
	v_lshlrev_b32_e32 v14, 16, v10
	v_and_b32_e32 v15, 0xffff0000, v10
	v_lshlrev_b32_e32 v10, 16, v11
	v_and_b32_e32 v11, 0xffff0000, v11
	v_lshrrev_b32_e32 v5, 31, v4
	v_ashrrev_i32_e32 v4, 1, v4
	v_pk_mul_f32 v[10:11], v[10:11], s[48:49] op_sel_hi:[1,0]
	v_add_u32_e32 v45, v4, v5
	v_cvt_pk_bf16_f32 v71, v10, v11
	v_lshlrev_b32_e32 v10, 16, v6
	v_and_b32_e32 v11, 0xffff0000, v6
	v_lshlrev_b32_e32 v6, 16, v7
	v_and_b32_e32 v7, 0xffff0000, v7
	v_mad_u64_u32 v[4:5], s[38:39], v45, -12, v[160:161]
	v_add_u32_e32 v164, 0x200, v160
	v_pk_mul_f32 v[6:7], v[6:7], s[48:49] op_sel_hi:[1,0]
	v_mul_hi_i32 v5, v164, s16
	v_cvt_pk_bf16_f32 v75, v6, v7
	v_lshrrev_b32_e32 v6, 31, v5
	v_ashrrev_i32_e32 v5, 1, v5
	s_mul_i32 s15, s4, 0xcc000
	v_add_u32_e32 v5, v5, v6
	v_pk_mul_f32 v[38:39], v[38:39], s[48:49] op_sel_hi:[1,0]
	v_pk_mul_f32 v[14:15], v[14:15], s[48:49] op_sel_hi:[1,0]
	s_mul_hi_i32 s5, s4, 0xcc000
	s_add_u32 s26, s90, s15
	v_mad_u64_u32 v[6:7], s[38:39], v5, -12, v[164:165]
	v_add_u32_e32 v162, 0x400, v160
	v_cvt_pk_bf16_f32 v66, v38, v39
	v_cvt_pk_bf16_f32 v70, v14, v15
	v_pk_mul_f32 v[8:9], v[8:9], s[48:49] op_sel_hi:[1,0]
	v_pk_mul_f32 v[10:11], v[10:11], s[48:49] op_sel_hi:[1,0]
	s_addc_u32 s27, s91, s5
	v_mul_hi_i32 v7, v162, s16
	v_lshlrev_b32_e32 v14, 3, v4
	v_lshlrev_b32_e32 v38, 3, v6
	v_pk_mul_f32 v[36:37], v[36:37], s[48:49] op_sel_hi:[1,0]
	v_pk_mul_f32 v[12:13], v[12:13], s[48:49] op_sel_hi:[1,0]
	v_cvt_pk_bf16_f32 v72, v8, v9
	v_cvt_pk_bf16_f32 v74, v10, v11
	v_lshrrev_b32_e32 v8, 31, v7
	v_ashrrev_i32_e32 v7, 1, v7
	v_mov_b64_e32 v[10:11], s[26:27]
	v_ashrrev_i32_e32 v15, 31, v14
	v_ashrrev_i32_e32 v39, 31, v38
	v_cvt_pk_bf16_f32 v64, v36, v37
	v_cvt_pk_bf16_f32 v68, v12, v13
	v_add_u32_e32 v7, v7, v8
	v_mad_i64_i32 v[12:13], s[26:27], v45, s17, v[10:11]
	v_lshlrev_b64 v[14:15], 1, v[14:15]
	v_mad_i64_i32 v[36:37], s[26:27], v5, s17, v[10:11]
	v_lshlrev_b64 v[38:39], 1, v[38:39]
	v_mad_u64_u32 v[8:9], s[38:39], v7, -12, v[162:163]
	v_lshl_add_u64 v[12:13], v[12:13], 0, v[14:15]
	v_lshl_add_u64 v[36:37], v[36:37], 0, v[38:39]
	s_barrier
; DI f32x16 zero16() { f32x16 z; for (int i = 0; i < 16; ++i) z[i] = 0.f; return z; }
; DI void phase_attn(const Params& p, int hf, bool skipctx, char* smem, int& rot) {
;     ...
;     const bf16_t* Kg = Kb + (size_t)(bl * 8 + head) * S * 96;
;     const bf16_t* Vg = VTb + (size_t)(bl * 8 + head) * 64 * S;
;     f32x16 o[2]; o[0] = zero16(); o[1] = zero16();
;     float m_run = -1e30f, l_run = 0.f;
;     uint4 ak0, ak1, ak2, av0, av1, bk0, bk1, bk2, bv0, bv1;
;     const int kr0 = tid / 12, kc0 = tid - kr0 * 12, kr1 = (tid + 512) / 12, kc1 = (tid + 512) - kr1 * 12, kr2 = (tid + 1024) / 12, kc2 = (tid + 1024) - kr2 * 12;
;     const int vr0 = tid >> 4, vr1 = (tid + 512) >> 4, vc = tid & 15;
;     ...
;     __syncthreads();
;     ATT_LOAD(ak0, ak1, ak2, av0, av1, 0);
;     ATT_LOAD(bk0, bk1, bk2, bv0, bv1, 1);
	global_load_dwordx4 v[76:79], v[12:13], off
	global_load_dwordx4 v[80:83], v[36:37], off
	v_lshlrev_b32_e32 v36, 3, v8
	s_mul_i32 s15, s4, 0x88000
	v_readlane_b32 s36, v252, 5
	v_ashrrev_i32_e32 v37, 31, v36
	s_mul_hi_i32 s5, s4, 0x88000
	v_readlane_b32 s37, v252, 6
	s_add_u32 s36, s36, s15
	v_mad_i64_i32 v[12:13], s[26:27], v7, s17, v[10:11]
	v_lshlrev_b64 v[36:37], 1, v[36:37]
	s_addc_u32 s37, s37, s5
	v_lshl_add_u64 v[12:13], v[12:13], 0, v[36:37]
	v_mov_b32_e32 v40, v42
	v_mov_b32_e32 v41, v16
	v_mov_b32_e32 v16, v43
	v_ashrrev_i32_e32 v9, 4, v160
	v_ashrrev_i32_e32 v50, 4, v164
	global_load_dwordx4 v[84:87], v[12:13], off
	v_mov_b64_e32 v[12:13], s[36:37]
	s_movk_i32 s16, 0x2200
	v_lshlrev_b32_e32 v165, 4, v160
	v_cvt_pk_bf16_f32 v100, v20, v21
	v_add_u32_e32 v20, 0x80, v5
	v_pk_add_f32 v[16:17], v[40:41], v[16:17] neg_lo:[0,1] neg_hi:[0,1]
	v_mad_i64_i32 v[40:41], s[26:27], v9, s16, v[12:13]
	v_and_b32_e32 v42, 0xf0, v165
	v_mov_b32_e32 v43, v221
	v_mad_i64_i32 v[12:13], s[26:27], v50, s16, v[12:13]
	v_cvt_pk_bf16_f32 v98, v18, v19
	v_cvt_pk_bf16_f32 v102, v22, v23
	v_add_u32_e32 v18, 0x80, v45
	v_mad_i64_i32 v[20:21], s[26:27], v20, s17, v[10:11]
	v_add_u32_e32 v22, 0x80, v7
	v_lshl_add_u64 v[40:41], v[40:41], 0, v[42:43]
	v_lshl_add_u64 v[12:13], v[12:13], 0, v[42:43]
	v_mad_i64_i32 v[18:19], s[26:27], v18, s17, v[10:11]
	v_lshl_add_u64 v[20:21], v[20:21], 0, v[38:39]
	v_mad_i64_i32 v[10:11], s[26:27], v22, s17, v[10:11]
	global_load_dwordx4 v[92:95], v[40:41], off
	global_load_dwordx4 v[104:107], v[12:13], off
	v_lshl_add_u64 v[18:19], v[18:19], 0, v[14:15]
	v_lshl_add_u64 v[10:11], v[10:11], 0, v[36:37]
	global_load_dwordx4 v[108:111], v[20:21], off
	global_load_dwordx4 v[116:119], v[10:11], off
	global_load_dwordx4 v[120:123], v[40:41], off offset:256
	global_load_dwordx4 v[112:115], v[18:19], off
	global_load_dwordx4 v[124:127], v[12:13], off offset:256
	v_lshlrev_b32_e32 v46, 16, v0
	v_and_b32_e32 v47, 0xffff0000, v0
	v_lshlrev_b32_e32 v0, 16, v1
	v_and_b32_e32 v1, 0xffff0000, v1
	v_pk_mul_f32 v[30:31], v[30:31], s[48:49] op_sel_hi:[1,0]
	v_pk_add_f32 v[32:33], v[48:49], v[32:33] neg_lo:[0,1] neg_hi:[0,1]
	v_pk_mul_f32 v[0:1], v[0:1], s[48:49] op_sel_hi:[1,0]
	v_lshlrev_b32_e32 v48, 16, v2
	v_and_b32_e32 v49, 0xffff0000, v2
	v_lshlrev_b32_e32 v2, 16, v3
	v_and_b32_e32 v3, 0xffff0000, v3
	v_pk_mul_f32 v[2:3], v[2:3], s[48:49] op_sel_hi:[1,0]
	v_cvt_pk_bf16_f32 v89, v0, v1
	v_pk_mul_f32 v[0:1], v[30:31], v[24:25] op_sel:[0,1] op_sel_hi:[1,0]
	v_cvt_pk_bf16_f32 v91, v2, v3
	v_mov_b32_e32 v2, v28
	v_mov_b32_e32 v3, v0
	v_mov_b32_e32 v0, v29
	v_pk_add_f32 v[0:1], v[2:3], v[0:1] neg_lo:[0,1] neg_hi:[0,1]
	v_pk_mul_f32 v[2:3], v[30:31], v[24:25]
	v_mul_lo_u32 v10, v45, s97
	v_mov_b32_e32 v24, v26
	v_mov_b32_e32 v25, v2
	v_mov_b32_e32 v2, v27
	v_add_u32_e32 v10, 0, v10
	v_lshlrev_b32_e32 v4, 4, v4
	v_pk_add_f32 v[2:3], v[24:25], v[2:3]
	v_add_u32_e32 v176, v10, v4
	v_mul_lo_u32 v4, v5, s97
	v_cvt_pk_bf16_f32 v103, v2, v3
	v_mad_i64_i32 v[2:3], s[26:27], v5, s17, 0
	v_add_u32_e32 v4, 0, v4
	v_lshlrev_b32_e32 v5, 4, v6
	v_add_u32_e32 v177, v4, v5
	v_mul_lo_u32 v4, v7, s97
	v_add_u32_e32 v4, 0, v4
	v_lshlrev_b32_e32 v5, 4, v8
	s_movk_i32 s20, 0x108
	v_cvt_pk_bf16_f32 v96, v16, v17
	v_cvt_pk_bf16_f32 v99, v0, v1
	v_mad_i64_i32 v[0:1], s[26:27], v45, s17, 0
	v_mad_i64_i32 v[16:17], s[26:27], v7, s17, 0
	v_add_u32_e32 v178, v4, v5
	v_mul_lo_u32 v4, v9, s20
	v_add_u32_e32 v5, 0, v4
	s_movk_i32 s26, 0x6800
	v_add3_u32 v179, v5, v42, s26
	v_mul_lo_u32 v5, v50, s20
	v_add_u32_e32 v6, 0, v5
	v_add3_u32 v180, v6, v42, s26
	v_or_b32_e32 v181, 32, v161
	v_or_b32_e32 v182, 64, v161
	v_or_b32_e32 v183, 0x60, v161
	v_readlane_b32 s26, v254, 35
	v_mul_u32_u24_e32 v19, 0x108, v44
	v_mad_u32_u24 v18, v44, s97, 0
	v_add_u32_e32 v21, s26, v4
	v_add_u32_e32 v22, s26, v5
	v_add_u32_e32 v23, s26, v161
	v_add_u32_e32 v24, s26, v181
	v_mov_b32_e32 v4, s26
	v_add_u32_e32 v25, s26, v182
	v_add_u32_e32 v26, s26, v183
	v_readlane_b32 s26, v254, 36
	v_mad_u32_u24 v184, v44, s20, v4
	v_add_u32_e32 v20, 0, v161
	v_add_u32_e32 v27, s26, v161
	v_add_u32_e32 v28, s26, v181
	v_mov_b32_e32 v4, s26
	v_add_u32_e32 v29, s26, v182
	v_add_u32_e32 v30, s26, v183
	s_add_u32 s26, s15, 0x1a49c300
	s_addc_u32 s27, s5, 0
	v_mad_u32_u24 v185, v44, s20, v4
	v_mov_b64_e32 v[4:5], s[26:27]
	v_mad_i64_i32 v[166:167], s[26:27], v9, s16, v[4:5]
	v_mad_i64_i32 v[168:169], s[26:27], v50, s16, v[4:5]
	v_mad_i64_i32 v[4:5], s[26:27], s4, v231, v[16:17]
	v_mad_i64_i32 v[2:3], s[26:27], s4, v231, v[2:3]
	v_mad_i64_i32 v[0:1], s[4:5], s4, v231, v[0:1]
	v_lshl_add_u64 v[174:175], v[0:1], 0, v[14:15]
	v_mov_b32_e32 v14, v221
	v_mov_b32_e32 v15, v221
	v_add_u32_e32 v186, v21, v42
	v_add_u32_e32 v187, v22, v42
	v_add_u32_e32 v188, v23, v19
	v_add_u32_e32 v16, v24, v19
	v_add_u32_e32 v17, v25, v19
	v_add_u32_e32 v21, v26, v19
	v_add_u32_e32 v22, v28, v19
	v_add_u32_e32 v23, v29, v19
	v_add_u32_e32 v24, v30, v19
	v_pk_mul_f32 v[46:47], v[46:47], s[48:49] op_sel_hi:[1,0]
	v_pk_mul_f32 v[48:49], v[48:49], s[48:49] op_sel_hi:[1,0]
	v_lshl_add_u64 v[170:171], v[4:5], 0, v[36:37]
	v_lshl_add_u64 v[172:173], v[2:3], 0, v[38:39]
	v_mov_b32_e32 v0, v221
	v_mov_b32_e32 v1, v221
	v_mov_b32_e32 v2, v221
	v_mov_b32_e32 v3, v221
	v_mov_b32_e32 v4, v221
	v_mov_b32_e32 v5, v221
	v_mov_b32_e32 v6, v221
	v_mov_b32_e32 v7, v221
	v_mov_b32_e32 v8, v221
	v_mov_b32_e32 v9, v221
	v_mov_b32_e32 v10, v221
	v_mov_b32_e32 v11, v221
	v_mov_b32_e32 v12, v221
	v_mov_b32_e32 v13, v221
	v_add_u32_e32 v189, v27, v19
	v_add_u32_e32 v190, v18, v220
	v_add_u32_e32 v191, v20, v19
	v_add_u32_e32 v194, 0x2000, v16
	v_add_u32_e32 v204, 0x2000, v17
	v_add_u32_e32 v206, 0x2000, v21
	v_add_u32_e32 v208, 0x2000, v22
	v_add_u32_e32 v210, 0x2000, v23
	v_add_u32_e32 v211, 0x2000, v24
	v_mov_b64_e32 v[30:31], v[14:15]
	v_cvt_pk_bf16_f32 v88, v46, v47
	v_cvt_pk_bf16_f32 v90, v48, v49
	v_cvt_pk_bf16_f32 v97, v32, v33
	v_cvt_pk_bf16_f32 v101, v34, v35
	v_or_b32_e32 v166, v166, v42
	v_or_b32_e32 v168, v168, v42
	s_mov_b32 s4, 0
	v_mov_b32_e32 v212, 0xf149f2ca
	v_mov_b32_e32 v213, 0
	v_mov_b64_e32 v[28:29], v[12:13]
	v_mov_b64_e32 v[26:27], v[10:11]
	v_mov_b64_e32 v[24:25], v[8:9]
	v_mov_b64_e32 v[22:23], v[6:7]
	v_mov_b64_e32 v[20:21], v[4:5]
	v_mov_b64_e32 v[18:19], v[2:3]
	v_mov_b64_e32 v[16:17], v[0:1]
	v_and_b32_e32 v200, 15, v192
	v_lshrrev_b32_e32 v201, 4, v192
	v_mul_u32_u24_e32 v179, 0x110, v201
	v_lshrrev_b32_e32 v202, 1, v200
	v_lshl_add_u32 v179, v202, 5, v179
	v_and_b32_e32 v202, 1, v200
	v_lshl_add_u32 v179, v202, 3, v179
	v_add_u32_e32 v179, 0x6800, v179
	v_add_u32_e32 v180, 0x2200, v179
	v_add_u32_e32 v186, 0xac00, v179
	v_add_u32_e32 v187, 0xac00, v180
	v_and_b32_e32 v200, 31, v192
	v_bfe_u32 v201, v192, 5, 1
	v_mul_u32_u24_e32 v191, 0x110, v200
	v_lshl_add_u32 v191, v201, 4, v191
	v_add_u32_e32 v191, 0x6800, v191
	s_waitcnt vmcnt(9)
; #define MFMA(a, b, c) __builtin_amdgcn_mfma_f32_32x32x16_bf16((a), (b), (c), 0, 0, 0)
; DI void phase_attn(const Params& p, int hf, bool skipctx, char* smem, int& rot) {
;     ...
;         bf16x8 kf[2][6];
; #pragma unroll
;         for (int kb = 0; kb < 2; ++kb)
; #pragma unroll
;           for (int ks = 0; ks < 6; ++ks) kf[kb][ks] = *(const bf16x8*)(sk + (kb * 32 + r) * KROW + (ks * 16 + h * 8) * 2);
;         __builtin_amdgcn_sched_barrier(0);
; #pragma unroll
;         for (int ks = 0; ks < 6; ++ks)
; #pragma unroll
;           for (int kb = 0; kb < 2; ++kb) st[kb] = MFMA(kf[kb][ks], qf[ks], st[kb]);
;         __builtin_amdgcn_sched_barrier(0);
;       }
;       bf16x8 vf[2][2][2];
; #pragma unroll
;       for (int kb = 0; kb < 2; ++kb)
; #pragma unroll
;         for (int s2 = 0; s2 < 2; ++s2)
; #pragma unroll
;           for (int dvb = 0; dvb < 2; ++dvb) {
;             const char* vp = sv + (dvb * 32 + r) * VROW + (kb * 32 + 16 * s2 + 4 * h) * 2;
;             const s16x4 lo = *(const s16x4*)vp, hi = *(const s16x4*)(vp + 16);
;             vf[kb][s2][dvb] = __builtin_shufflevector(lo, hi, 0, 1, 2, 3, 4, 5, 6, 7);
;           }
;       float mx = st[0][0];
; #pragma unroll
;       for (int i = 0; i < 16; ++i) { mx = fmaxf(mx, st[0][i]); mx = fmaxf(mx, st[1][i]); }
;       if (__any(mx > m_run + 8.f)) {
;     ...
;     __syncthreads();
;     ATT_LOAD(ak0, ak1, ak2, av0, av1, 0);
;     ATT_LOAD(bk0, bk1, bk2, bv0, bv1, 1);
;     ATT_WRITE(ak0, ak1, ak2, av0, av1, 0);
;     __syncthreads();
;     for (int kt = 0; kt < nkt; kt += 2) {
;       if (kt + 2 < nkt) ATT_LOAD(ak0, ak1, ak2, av0, av1, kt + 2);
;       compute(0, 0); compute(0, 1);
	ds_write_b128 v176, v[76:79]
	s_waitcnt vmcnt(8)
	ds_write_b128 v177, v[80:83]
	s_waitcnt vmcnt(7)
	ds_write_b128 v178, v[84:87]
	s_waitcnt vmcnt(6)
	ds_write_b64 v179, v[92:93] offset:0
	ds_write_b64 v179, v[94:95] offset:16
	s_waitcnt vmcnt(5)
	ds_write_b64 v179, v[104:105] offset:8704
	ds_write_b64 v179, v[106:107] offset:8720
	s_waitcnt lgkmcnt(0)
	s_barrier
	v_mov_b32_e32 v194, v176
	v_mov_b32_e32 v204, v177
	v_mov_b32_e32 v206, v178
	v_mov_b32_e32 v208, v179
	v_mov_b32_e32 v210, v190
	v_mov_b32_e32 v211, v191
	v_mov_b32_e32 v220, 0xf149f2ca
	v_mov_b32_e32 v176, 0
	v_mov_b32_e32 v177, 0
	v_mov_b32_e32 v178, 0
	v_mov_b32_e32 v179, 0
	v_mov_b32_e32 v180, 0
	v_mov_b32_e32 v181, 0
	v_mov_b32_e32 v182, 0
	v_mov_b32_e32 v183, 0
	v_mov_b32_e32 v184, 0
	v_mov_b32_e32 v185, 0
	v_mov_b32_e32 v186, 0
	v_mov_b32_e32 v187, 0
	v_mov_b32_e32 v188, 0
	v_mov_b32_e32 v189, 0
	v_mov_b32_e32 v190, 0
	v_mov_b32_e32 v191, 0
.LBB0_795:
	ds_read_b128 v[32:35], v210
	ds_read_b128 v[128:131], v210 offset:32
	ds_read_b128 v[132:135], v210 offset:64
	ds_read_b128 v[136:139], v210 offset:96
	ds_read_b128 v[140:143], v210 offset:128
	ds_read_b128 v[144:147], v210 offset:160
	ds_read_b128 v[36:39], v210 offset:6656
	ds_read_b128 v[148:151], v210 offset:6688
	ds_read_b128 v[152:155], v210 offset:6720
	ds_read_b128 v[156:159], v210 offset:6752
	ds_read_b128 v[214:217], v210 offset:6784
	ds_read_b128 v[234:237], v210 offset:6816
	s_add_i32 s15, s4, 2
	s_cmp_lt_u32 s15, s13
	s_cselect_b64 s[36:37], -1, 0
	s_cmp_ge_u32 s15, s13
	s_cselect_b64 s[26:27], -1, 0
	s_and_b64 vcc, exec, s[26:27]
	s_cbranch_vccnz .LBB0_797
	v_lshl_add_u64 v[200:201], s[94:95], 0, v[174:175]
	v_add_co_u32_e32 v200, vcc, 0x18b28000, v200
	v_lshl_add_u64 v[202:203], s[94:95], 0, v[172:173]
	s_nop 0
	v_addc_co_u32_e32 v201, vcc, 0, v201, vcc
	v_add_co_u32_e32 v202, vcc, 0x18b28000, v202
	s_nop 1
	v_addc_co_u32_e32 v203, vcc, 0, v203, vcc
	global_load_dwordx4 v[76:79], v[200:201], off
	global_load_dwordx4 v[80:83], v[202:203], off
	v_lshl_add_u64 v[200:201], s[94:95], 0, v[170:171]
	v_add_co_u32_e32 v200, vcc, 0x18b28000, v200
	v_lshl_add_u64 v[202:203], s[94:95], 0, v[166:167]
	s_nop 0
	v_addc_co_u32_e32 v201, vcc, 0, v201, vcc
	global_load_dwordx4 v[84:87], v[200:201], off
	global_load_dwordx4 v[92:95], v[202:203], off offset:-256
	v_lshl_add_u64 v[200:201], s[94:95], 0, v[168:169]
	global_load_dwordx4 v[104:107], v[200:201], off offset:-256
.LBB0_797:
	s_waitcnt lgkmcnt(11)
	v_mfma_f32_32x32x16_bf16 v[48:63], v[32:35], v[64:67], v[176:191]
	s_waitcnt lgkmcnt(5)
	v_mfma_f32_32x32x16_bf16 v[32:47], v[36:39], v[64:67], v[176:191]
	v_mfma_f32_32x32x16_bf16 v[48:63], v[128:131], v[68:71], v[48:63]
	s_waitcnt lgkmcnt(4)
	v_mfma_f32_32x32x16_bf16 v[32:47], v[148:151], v[68:71], v[32:47]
	v_mfma_f32_32x32x16_bf16 v[48:63], v[132:135], v[72:75], v[48:63]
	s_waitcnt lgkmcnt(3)
	v_mfma_f32_32x32x16_bf16 v[32:47], v[152:155], v[72:75], v[32:47]
	v_mfma_f32_32x32x16_bf16 v[48:63], v[136:139], v[88:91], v[48:63]
	s_waitcnt lgkmcnt(2)
	v_mfma_f32_32x32x16_bf16 v[32:47], v[156:159], v[88:91], v[32:47]
	v_mfma_f32_32x32x16_bf16 v[48:63], v[140:143], v[96:99], v[48:63]
	s_waitcnt lgkmcnt(1)
	v_mfma_f32_32x32x16_bf16 v[32:47], v[214:217], v[96:99], v[32:47]
	v_mfma_f32_32x32x16_bf16 v[48:63], v[144:147], v[100:103], v[48:63]
	s_waitcnt lgkmcnt(0)
	v_mfma_f32_32x32x16_bf16 v[32:47], v[234:237], v[100:103], v[32:47]
	s_nop 3
	ds_read_b128 v[156:159], v211 offset:0
	ds_read_b128 v[148:151], v211 offset:32
	ds_read_b128 v[152:155], v211 offset:8704
	ds_read_b128 v[144:147], v211 offset:8736
	ds_read_b128 v[140:143], v211 offset:64
	ds_read_b128 v[136:139], v211 offset:8768
	ds_read_b128 v[132:135], v211 offset:96
	ds_read_b128 v[128:131], v211 offset:8800
	v_max_f32_e32 v195, v32, v32
	v_max_f32_e32 v200, v48, v48
	v_max_f32_e32 v195, v200, v195
	v_max3_f32 v195, v195, v49, v33
	v_max3_f32 v195, v195, v50, v34
	v_max3_f32 v195, v195, v51, v35
	v_max3_f32 v195, v195, v52, v36
	v_max3_f32 v195, v195, v53, v37
	v_max3_f32 v195, v195, v54, v38
	v_max3_f32 v195, v195, v55, v39
	v_max3_f32 v195, v195, v56, v40
	v_max3_f32 v195, v195, v57, v41
	v_max3_f32 v195, v195, v58, v42
	v_max3_f32 v195, v195, v59, v43
	v_max3_f32 v195, v195, v60, v44
	v_max3_f32 v195, v195, v61, v45
	v_max3_f32 v195, v195, v62, v46
	v_max3_f32 v217, v195, v63, v47
	v_cmp_gt_f32_e32 vcc, v217, v220
	s_cbranch_vccz .LBB0_799
; DI float fexp2(float x) { return __builtin_amdgcn_exp2f(x); }
; DI void phase_attn(const Params& p, int hf, bool skipctx, char* smem, int& rot) {
;     ...
;       if (__any(mx > m_run + 8.f)) {
;         mx = fmaxf(mx, __shfl_xor(mx, 32));
;         const float m_new = fmaxf(m_run, mx);
;         const float alpha = fexp2(m_run - m_new);
;         m_run = m_new;
;         l_run *= alpha;
; #pragma unroll
;         for (int i = 0; i < 16; ++i) { o[0][i] *= alpha; o[1][i] *= alpha; }
;       }
;       float ps = 0.f;
; #pragma unroll
;       for (int kb = 0; kb < 2; ++kb)
; #pragma unroll
;         for (int i = 0; i < 16; ++i) { const float e = fexp2(st[kb][i] - m_run); st[kb][i] = e; ps += e; }
	v_sub_f32_e32 v217, v217, v176
	v_cmp_lt_i32_e32 vcc, v224, v207
	s_nop 1
	v_cndmask_b32_e32 v195, v205, v224, vcc
	v_lshlrev_b32_e32 v195, 2, v195
	ds_bpermute_b32 v195, v195, v217
	s_waitcnt lgkmcnt(0)
	v_max3_f32 v195, v212, v217, v195
	v_sub_f32_e32 v200, v212, v195
	v_exp_f32_e32 v200, v200
	v_mov_b32_e32 v212, v195
	v_mul_f32_e32 v213, v213, v200
	v_pk_mul_f32 v[30:31], v[30:31], v[200:201] op_sel_hi:[1,0]
	v_pk_mul_f32 v[28:29], v[28:29], v[200:201] op_sel_hi:[1,0]
	v_pk_mul_f32 v[26:27], v[26:27], v[200:201] op_sel_hi:[1,0]
	v_pk_mul_f32 v[24:25], v[24:25], v[200:201] op_sel_hi:[1,0]
	v_pk_mul_f32 v[22:23], v[22:23], v[200:201] op_sel_hi:[1,0]
	v_pk_mul_f32 v[20:21], v[20:21], v[200:201] op_sel_hi:[1,0]
	v_pk_mul_f32 v[18:19], v[18:19], v[200:201] op_sel_hi:[1,0]
	v_pk_mul_f32 v[16:17], v[16:17], v[200:201] op_sel_hi:[1,0]
	v_pk_mul_f32 v[14:15], v[14:15], v[200:201] op_sel_hi:[1,0]
	v_pk_mul_f32 v[12:13], v[12:13], v[200:201] op_sel_hi:[1,0]
	v_pk_mul_f32 v[10:11], v[10:11], v[200:201] op_sel_hi:[1,0]
	v_pk_mul_f32 v[8:9], v[8:9], v[200:201] op_sel_hi:[1,0]
	v_pk_mul_f32 v[6:7], v[6:7], v[200:201] op_sel_hi:[1,0]
	v_pk_mul_f32 v[4:5], v[4:5], v[200:201] op_sel_hi:[1,0]
	v_pk_mul_f32 v[2:3], v[2:3], v[200:201] op_sel_hi:[1,0]
	v_pk_mul_f32 v[0:1], v[0:1], v[200:201] op_sel_hi:[1,0]
	v_add_f32_e32 v202, v195, v176
	v_sub_f32_e32 v32, v32, v202
	v_sub_f32_e32 v33, v33, v202
	v_sub_f32_e32 v34, v34, v202
	v_sub_f32_e32 v35, v35, v202
	v_sub_f32_e32 v36, v36, v202
	v_sub_f32_e32 v37, v37, v202
	v_sub_f32_e32 v38, v38, v202
	v_sub_f32_e32 v39, v39, v202
	v_sub_f32_e32 v40, v40, v202
	v_sub_f32_e32 v41, v41, v202
	v_sub_f32_e32 v42, v42, v202
	v_sub_f32_e32 v43, v43, v202
	v_sub_f32_e32 v44, v44, v202
	v_sub_f32_e32 v45, v45, v202
	v_sub_f32_e32 v46, v46, v202
	v_sub_f32_e32 v47, v47, v202
	v_sub_f32_e32 v48, v48, v202
	v_sub_f32_e32 v49, v49, v202
	v_sub_f32_e32 v50, v50, v202
	v_sub_f32_e32 v51, v51, v202
	v_sub_f32_e32 v52, v52, v202
	v_sub_f32_e32 v53, v53, v202
	v_sub_f32_e32 v54, v54, v202
	v_sub_f32_e32 v55, v55, v202
	v_sub_f32_e32 v56, v56, v202
	v_sub_f32_e32 v57, v57, v202
	v_sub_f32_e32 v58, v58, v202
	v_sub_f32_e32 v59, v59, v202
	v_sub_f32_e32 v60, v60, v202
	v_sub_f32_e32 v61, v61, v202
	v_sub_f32_e32 v62, v62, v202
	v_sub_f32_e32 v63, v63, v202
	v_sub_f32_e32 v176, 0, v195
	v_sub_f32_e32 v177, 0, v195
	v_sub_f32_e32 v178, 0, v195
	v_sub_f32_e32 v179, 0, v195
	v_sub_f32_e32 v180, 0, v195
	v_sub_f32_e32 v181, 0, v195
	v_sub_f32_e32 v182, 0, v195
	v_sub_f32_e32 v183, 0, v195
	v_sub_f32_e32 v184, 0, v195
	v_sub_f32_e32 v185, 0, v195
	v_sub_f32_e32 v186, 0, v195
	v_sub_f32_e32 v187, 0, v195
	v_sub_f32_e32 v188, 0, v195
	v_sub_f32_e32 v189, 0, v195
	v_sub_f32_e32 v190, 0, v195
	v_sub_f32_e32 v191, 0, v195
	v_mov_b32_e32 v220, 0x41000000
.LBB0_799:
	v_exp_f32_e32 v48, v48
	v_exp_f32_e32 v49, v49
	v_exp_f32_e32 v50, v50
	v_exp_f32_e32 v51, v51
	v_add_f32_e32 v195, 0, v48
	v_exp_f32_e32 v52, v52
	v_add_f32_e32 v195, v49, v195
	v_exp_f32_e32 v53, v53
	v_add_f32_e32 v195, v50, v195
	v_exp_f32_e32 v54, v54
	v_add_f32_e32 v195, v51, v195
	v_exp_f32_e32 v55, v55
	v_add_f32_e32 v195, v52, v195
	v_exp_f32_e32 v56, v56
	v_add_f32_e32 v195, v53, v195
	v_exp_f32_e32 v57, v57
	v_add_f32_e32 v195, v54, v195
	v_exp_f32_e32 v58, v58
	v_add_f32_e32 v195, v55, v195
	v_exp_f32_e32 v59, v59
	v_add_f32_e32 v195, v56, v195
	v_exp_f32_e32 v60, v60
	v_add_f32_e32 v195, v57, v195
	v_exp_f32_e32 v61, v61
	v_add_f32_e32 v195, v58, v195
	v_exp_f32_e32 v62, v62
	v_add_f32_e32 v195, v59, v195
	v_exp_f32_e32 v63, v63
	v_add_f32_e32 v195, v60, v195
	v_exp_f32_e32 v200, v32
	v_add_f32_e32 v195, v61, v195
	v_exp_f32_e32 v201, v33
	v_add_f32_e32 v32, v62, v195
	v_exp_f32_e32 v195, v34
	v_add_f32_e32 v32, v63, v32
	v_exp_f32_e32 v202, v35
	v_add_f32_e32 v32, v200, v32
	v_exp_f32_e32 v36, v36
	v_add_f32_e32 v32, v201, v32
	v_exp_f32_e32 v37, v37
	v_add_f32_e32 v32, v195, v32
	v_add_f32_e32 v32, v202, v32
	v_add_f32_e32 v32, v36, v32
	v_add_f32_e32 v203, v37, v32
	v_cvt_pk_bf16_f32 v32, v48, v49
	v_cvt_pk_bf16_f32 v33, v50, v51
	v_cvt_pk_bf16_f32 v34, v52, v53
	v_cvt_pk_bf16_f32 v35, v54, v55
	v_exp_f32_e32 v38, v38
	s_waitcnt lgkmcnt(7)
	v_mfma_f32_32x32x16_bf16 v[16:31], v[156:159], v[32:35], v[16:31]
	v_exp_f32_e32 v39, v39
	v_exp_f32_e32 v40, v40
	v_add_f32_e32 v48, v38, v203
	v_exp_f32_e32 v42, v42
	s_waitcnt lgkmcnt(5)
	v_mfma_f32_32x32x16_bf16 v[0:15], v[152:155], v[32:35], v[0:15]
	v_exp_f32_e32 v41, v41
	v_cvt_pk_bf16_f32 v32, v56, v57
	v_cvt_pk_bf16_f32 v33, v58, v59
	v_cvt_pk_bf16_f32 v34, v60, v61
	v_cvt_pk_bf16_f32 v35, v62, v63
	v_add_f32_e32 v48, v39, v48
	v_mfma_f32_32x32x16_bf16 v[16:31], v[148:151], v[32:35], v[16:31]
	v_exp_f32_e32 v43, v43
	v_add_f32_e32 v48, v40, v48
	v_exp_f32_e32 v44, v44
	v_add_f32_e32 v48, v41, v48
	s_waitcnt lgkmcnt(4)
	v_mfma_f32_32x32x16_bf16 v[0:15], v[144:147], v[32:35], v[0:15]
	v_add_f32_e32 v32, v42, v48
	v_add_f32_e32 v32, v43, v32
	v_add_f32_e32 v48, v44, v32
	v_cvt_pk_bf16_f32 v32, v200, v201
	v_cvt_pk_bf16_f32 v33, v195, v202
	v_cvt_pk_bf16_f32 v34, v36, v37
	v_cvt_pk_bf16_f32 v35, v38, v39
	v_exp_f32_e32 v36, v45
	s_waitcnt lgkmcnt(3)
	v_mfma_f32_32x32x16_bf16 v[16:31], v[140:143], v[32:35], v[16:31]
	v_exp_f32_e32 v37, v46
	v_exp_f32_e32 v38, v47
	v_add_f32_e32 v39, v36, v48
	s_waitcnt lgkmcnt(2)
	v_mfma_f32_32x32x16_bf16 v[0:15], v[136:139], v[32:35], v[0:15]
	v_add_f32_e32 v32, v37, v39
	v_add_f32_e32 v32, v38, v32
	v_add_f32_e32 v213, v213, v32
	v_cvt_pk_bf16_f32 v32, v40, v41
	v_cvt_pk_bf16_f32 v33, v42, v43
	v_cvt_pk_bf16_f32 v34, v44, v36
	v_cvt_pk_bf16_f32 v35, v37, v38
	s_waitcnt lgkmcnt(1)
; #define MFMA(a, b, c) __builtin_amdgcn_mfma_f32_32x32x16_bf16((a), (b), (c), 0, 0, 0)
; DI float fexp2(float x) { return __builtin_amdgcn_exp2f(x); }
; DI void phase_attn(const Params& p, int hf, bool skipctx, char* smem, int& rot) {
;     ...
;         bf16x8 kf[2][6];
; #pragma unroll
;         for (int kb = 0; kb < 2; ++kb)
; #pragma unroll
;           for (int ks = 0; ks < 6; ++ks) kf[kb][ks] = *(const bf16x8*)(sk + (kb * 32 + r) * KROW + (ks * 16 + h * 8) * 2);
;         __builtin_amdgcn_sched_barrier(0);
; #pragma unroll
;         for (int ks = 0; ks < 6; ++ks)
; #pragma unroll
;           for (int kb = 0; kb < 2; ++kb) st[kb] = MFMA(kf[kb][ks], qf[ks], st[kb]);
;         __builtin_amdgcn_sched_barrier(0);
;       }
;       bf16x8 vf[2][2][2];
; #pragma unroll
;       for (int kb = 0; kb < 2; ++kb)
; #pragma unroll
;         for (int s2 = 0; s2 < 2; ++s2)
; #pragma unroll
;           for (int dvb = 0; dvb < 2; ++dvb) {
;             const char* vp = sv + (dvb * 32 + r) * VROW + (kb * 32 + 16 * s2 + 4 * h) * 2;
;             const s16x4 lo = *(const s16x4*)vp, hi = *(const s16x4*)(vp + 16);
;             vf[kb][s2][dvb] = __builtin_shufflevector(lo, hi, 0, 1, 2, 3, 4, 5, 6, 7);
;           }
;       float mx = st[0][0];
; #pragma unroll
;       for (int i = 0; i < 16; ++i) { mx = fmaxf(mx, st[0][i]); mx = fmaxf(mx, st[1][i]); }
;       if (__any(mx > m_run + 8.f)) {
;         mx = fmaxf(mx, __shfl_xor(mx, 32));
;         const float m_new = fmaxf(m_run, mx);
;         const float alpha = fexp2(m_run - m_new);
;         m_run = m_new;
;         l_run *= alpha;
; #pragma unroll
;         for (int i = 0; i < 16; ++i) { o[0][i] *= alpha; o[1][i] *= alpha; }
;       }
;       float ps = 0.f;
; #pragma unroll
;       for (int kb = 0; kb < 2; ++kb)
; #pragma unroll
;         for (int i = 0; i < 16; ++i) { const float e = fexp2(st[kb][i] - m_run); st[kb][i] = e; ps += e; }
;       l_run += ps;
; #pragma unroll
;       for (int kb = 0; kb < 2; ++kb)
; #pragma unroll
;         for (int s2 = 0; s2 < 2; ++s2) {
;           const bf16x8 pb = pack8(st[kb][8 * s2 + 0], st[kb][8 * s2 + 1], st[kb][8 * s2 + 2], st[kb][8 * s2 + 3], st[kb][8 * s2 + 4], st[kb][8 * s2 + 5], st[kb][8 * s2 + 6], st[kb][8 * s2 + 7]);
; #pragma unroll
;           for (int dvb = 0; dvb < 2; ++dvb) o[dvb] = MFMA(vf[kb][s2][dvb], pb, o[dvb]);
	s_nop 0
	v_mfma_f32_32x32x16_bf16 v[16:31], v[132:135], v[32:35], v[16:31]
	ds_read_b128 v[36:39], v210 offset:13312
	ds_read_b128 v[132:135], v210 offset:13344
	ds_read_b128 v[136:139], v210 offset:13376
	ds_read_b128 v[140:143], v210 offset:13408
	ds_read_b128 v[144:147], v210 offset:13440
	ds_read_b128 v[148:151], v210 offset:13472
	ds_read_b128 v[40:43], v210 offset:19968
	ds_read_b128 v[152:155], v210 offset:20000
	ds_read_b128 v[156:159], v210 offset:20032
	ds_read_b128 v[234:237], v210 offset:20064
	ds_read_b128 v[238:241], v210 offset:20096
	ds_read_b128 v[242:245], v210 offset:20128
	s_waitcnt lgkmcnt(12)
	v_mfma_f32_32x32x16_bf16 v[0:15], v[128:131], v[32:35], v[0:15]
	s_waitcnt lgkmcnt(11)
	v_mfma_f32_32x32x16_bf16 v[48:63], v[36:39], v[64:67], v[176:191]
	s_waitcnt lgkmcnt(5)
	v_mfma_f32_32x32x16_bf16 v[32:47], v[40:43], v[64:67], v[176:191]
	v_mfma_f32_32x32x16_bf16 v[48:63], v[132:135], v[68:71], v[48:63]
	s_waitcnt lgkmcnt(4)
	v_mfma_f32_32x32x16_bf16 v[32:47], v[152:155], v[68:71], v[32:47]
	v_mfma_f32_32x32x16_bf16 v[48:63], v[136:139], v[72:75], v[48:63]
	s_waitcnt lgkmcnt(3)
	v_mfma_f32_32x32x16_bf16 v[32:47], v[156:159], v[72:75], v[32:47]
	v_mfma_f32_32x32x16_bf16 v[48:63], v[140:143], v[88:91], v[48:63]
	s_waitcnt lgkmcnt(2)
	v_mfma_f32_32x32x16_bf16 v[32:47], v[234:237], v[88:91], v[32:47]
	v_mfma_f32_32x32x16_bf16 v[48:63], v[144:147], v[96:99], v[48:63]
	s_waitcnt lgkmcnt(1)
	v_mfma_f32_32x32x16_bf16 v[32:47], v[238:241], v[96:99], v[32:47]
	v_mfma_f32_32x32x16_bf16 v[48:63], v[148:151], v[100:103], v[48:63]
	s_waitcnt lgkmcnt(0)
	v_mfma_f32_32x32x16_bf16 v[32:47], v[242:245], v[100:103], v[32:47]
	s_nop 3
	ds_read_b128 v[156:159], v211 offset:128
	ds_read_b128 v[148:151], v211 offset:160
	ds_read_b128 v[152:155], v211 offset:8832
	ds_read_b128 v[144:147], v211 offset:8864
	ds_read_b128 v[140:143], v211 offset:192
	ds_read_b128 v[136:139], v211 offset:8896
	ds_read_b128 v[128:131], v211 offset:224
	ds_read_b128 v[132:135], v211 offset:8928
	v_max_f32_e32 v195, v32, v32
	v_max_f32_e32 v200, v48, v48
	v_max_f32_e32 v195, v200, v195
	v_max3_f32 v195, v195, v49, v33
	v_max3_f32 v195, v195, v50, v34
	v_max3_f32 v195, v195, v51, v35
	v_max3_f32 v195, v195, v52, v36
	v_max3_f32 v195, v195, v53, v37
	v_max3_f32 v195, v195, v54, v38
	v_max3_f32 v195, v195, v55, v39
	v_max3_f32 v195, v195, v56, v40
	v_max3_f32 v195, v195, v57, v41
	v_max3_f32 v195, v195, v58, v42
	v_max3_f32 v195, v195, v59, v43
	v_max3_f32 v195, v195, v60, v44
	v_max3_f32 v195, v195, v61, v45
	v_max3_f32 v195, v195, v62, v46
	v_max3_f32 v214, v195, v63, v47
	v_cmp_gt_f32_e32 vcc, v214, v220
	s_cbranch_vccz .LBB0_801
	v_sub_f32_e32 v214, v214, v176
	v_cmp_lt_i32_e32 vcc, v224, v207
	s_nop 1
	v_cndmask_b32_e32 v195, v205, v224, vcc
	v_lshlrev_b32_e32 v195, 2, v195
	ds_bpermute_b32 v195, v195, v214
	s_waitcnt lgkmcnt(0)
	v_max3_f32 v195, v212, v214, v195
	v_sub_f32_e32 v200, v212, v195
	v_exp_f32_e32 v200, v200
	v_mov_b32_e32 v212, v195
	v_mul_f32_e32 v213, v213, v200
	v_pk_mul_f32 v[30:31], v[30:31], v[200:201] op_sel_hi:[1,0]
	v_pk_mul_f32 v[28:29], v[28:29], v[200:201] op_sel_hi:[1,0]
	v_pk_mul_f32 v[26:27], v[26:27], v[200:201] op_sel_hi:[1,0]
	v_pk_mul_f32 v[24:25], v[24:25], v[200:201] op_sel_hi:[1,0]
	v_pk_mul_f32 v[22:23], v[22:23], v[200:201] op_sel_hi:[1,0]
	v_pk_mul_f32 v[20:21], v[20:21], v[200:201] op_sel_hi:[1,0]
	v_pk_mul_f32 v[18:19], v[18:19], v[200:201] op_sel_hi:[1,0]
	v_pk_mul_f32 v[16:17], v[16:17], v[200:201] op_sel_hi:[1,0]
	v_pk_mul_f32 v[14:15], v[14:15], v[200:201] op_sel_hi:[1,0]
	v_pk_mul_f32 v[12:13], v[12:13], v[200:201] op_sel_hi:[1,0]
	v_pk_mul_f32 v[10:11], v[10:11], v[200:201] op_sel_hi:[1,0]
	v_pk_mul_f32 v[8:9], v[8:9], v[200:201] op_sel_hi:[1,0]
	v_pk_mul_f32 v[6:7], v[6:7], v[200:201] op_sel_hi:[1,0]
	v_pk_mul_f32 v[4:5], v[4:5], v[200:201] op_sel_hi:[1,0]
	v_pk_mul_f32 v[2:3], v[2:3], v[200:201] op_sel_hi:[1,0]
	v_pk_mul_f32 v[0:1], v[0:1], v[200:201] op_sel_hi:[1,0]
	v_add_f32_e32 v202, v195, v176
	v_sub_f32_e32 v32, v32, v202
	v_sub_f32_e32 v33, v33, v202
	v_sub_f32_e32 v34, v34, v202
	v_sub_f32_e32 v35, v35, v202
	v_sub_f32_e32 v36, v36, v202
	v_sub_f32_e32 v37, v37, v202
	v_sub_f32_e32 v38, v38, v202
	v_sub_f32_e32 v39, v39, v202
	v_sub_f32_e32 v40, v40, v202
	v_sub_f32_e32 v41, v41, v202
	v_sub_f32_e32 v42, v42, v202
	v_sub_f32_e32 v43, v43, v202
	v_sub_f32_e32 v44, v44, v202
	v_sub_f32_e32 v45, v45, v202
	v_sub_f32_e32 v46, v46, v202
	v_sub_f32_e32 v47, v47, v202
	v_sub_f32_e32 v48, v48, v202
	v_sub_f32_e32 v49, v49, v202
	v_sub_f32_e32 v50, v50, v202
	v_sub_f32_e32 v51, v51, v202
	v_sub_f32_e32 v52, v52, v202
	v_sub_f32_e32 v53, v53, v202
	v_sub_f32_e32 v54, v54, v202
	v_sub_f32_e32 v55, v55, v202
	v_sub_f32_e32 v56, v56, v202
	v_sub_f32_e32 v57, v57, v202
	v_sub_f32_e32 v58, v58, v202
	v_sub_f32_e32 v59, v59, v202
	v_sub_f32_e32 v60, v60, v202
	v_sub_f32_e32 v61, v61, v202
	v_sub_f32_e32 v62, v62, v202
	v_sub_f32_e32 v63, v63, v202
	v_sub_f32_e32 v176, 0, v195
	v_sub_f32_e32 v177, 0, v195
	v_sub_f32_e32 v178, 0, v195
	v_sub_f32_e32 v179, 0, v195
	v_sub_f32_e32 v180, 0, v195
	v_sub_f32_e32 v181, 0, v195
	v_sub_f32_e32 v182, 0, v195
	v_sub_f32_e32 v183, 0, v195
	v_sub_f32_e32 v184, 0, v195
	v_sub_f32_e32 v185, 0, v195
	v_sub_f32_e32 v186, 0, v195
	v_sub_f32_e32 v187, 0, v195
	v_sub_f32_e32 v188, 0, v195
	v_sub_f32_e32 v189, 0, v195
	v_sub_f32_e32 v190, 0, v195
	v_sub_f32_e32 v191, 0, v195
	v_mov_b32_e32 v220, 0x41000000
; #define MFMA(a, b, c) __builtin_amdgcn_mfma_f32_32x32x16_bf16((a), (b), (c), 0, 0, 0)
; DI float fexp2(float x) { return __builtin_amdgcn_exp2f(x); }
; DI void phase_attn(const Params& p, int hf, bool skipctx, char* smem, int& rot) {
;     ...
;       float ps = 0.f;
; #pragma unroll
;       for (int kb = 0; kb < 2; ++kb)
; #pragma unroll
;         for (int i = 0; i < 16; ++i) { const float e = fexp2(st[kb][i] - m_run); st[kb][i] = e; ps += e; }
;       l_run += ps;
; #pragma unroll
;       for (int kb = 0; kb < 2; ++kb)
; #pragma unroll
;         for (int s2 = 0; s2 < 2; ++s2) {
;           const bf16x8 pb = pack8(st[kb][8 * s2 + 0], st[kb][8 * s2 + 1], st[kb][8 * s2 + 2], st[kb][8 * s2 + 3], st[kb][8 * s2 + 4], st[kb][8 * s2 + 5], st[kb][8 * s2 + 6], st[kb][8 * s2 + 7]);
; #pragma unroll
;           for (int dvb = 0; dvb < 2; ++dvb) o[dvb] = MFMA(vf[kb][s2][dvb], pb, o[dvb]);
;         }
;     };
;     __syncthreads();
;     ATT_LOAD(ak0, ak1, ak2, av0, av1, 0);
;     ATT_LOAD(bk0, bk1, bk2, bv0, bv1, 1);
;     ATT_WRITE(ak0, ak1, ak2, av0, av1, 0);
;     __syncthreads();
;     for (int kt = 0; kt < nkt; kt += 2) {
;       if (kt + 2 < nkt) ATT_LOAD(ak0, ak1, ak2, av0, av1, kt + 2);
;       compute(0, 0); compute(0, 1);
;       ATT_WRITE(bk0, bk1, bk2, bv0, bv1, 1);
;       __syncthreads();
;       if (kt + 3 < nkt) ATT_LOAD(bk0, bk1, bk2, bv0, bv1, kt + 3);
;       compute(1, 0); compute(1, 1);
.LBB0_801:
	v_exp_f32_e32 v48, v48
	v_exp_f32_e32 v49, v49
	v_exp_f32_e32 v50, v50
	v_exp_f32_e32 v51, v51
	v_exp_f32_e32 v52, v52
	v_exp_f32_e32 v53, v53
	v_exp_f32_e32 v54, v54
	v_exp_f32_e32 v55, v55
	v_cvt_pk_bf16_f32 v214, v48, v49
	v_cvt_pk_bf16_f32 v215, v50, v51
	v_cvt_pk_bf16_f32 v216, v52, v53
	v_cvt_pk_bf16_f32 v217, v54, v55
	s_waitcnt lgkmcnt(7)
	v_mfma_f32_32x32x16_bf16 v[16:31], v[156:159], v[214:217], v[16:31]
	v_exp_f32_e32 v56, v56
	s_waitcnt lgkmcnt(5)
	v_mfma_f32_32x32x16_bf16 v[0:15], v[152:155], v[214:217], v[0:15]
	v_exp_f32_e32 v57, v57
	v_exp_f32_e32 v58, v58
	v_exp_f32_e32 v59, v59
	v_exp_f32_e32 v60, v60
	v_exp_f32_e32 v61, v61
	v_exp_f32_e32 v62, v62
	v_exp_f32_e32 v63, v63
	v_cvt_pk_bf16_f32 v152, v56, v57
	v_cvt_pk_bf16_f32 v153, v58, v59
	v_cvt_pk_bf16_f32 v154, v60, v61
	v_cvt_pk_bf16_f32 v155, v62, v63
	v_mfma_f32_32x32x16_bf16 v[16:31], v[148:151], v[152:155], v[16:31]
	v_exp_f32_e32 v32, v32
	s_waitcnt lgkmcnt(4)
	v_mfma_f32_32x32x16_bf16 v[0:15], v[144:147], v[152:155], v[0:15]
	v_exp_f32_e32 v33, v33
	v_exp_f32_e32 v34, v34
	v_exp_f32_e32 v35, v35
	v_exp_f32_e32 v36, v36
	v_exp_f32_e32 v37, v37
	v_exp_f32_e32 v38, v38
	v_exp_f32_e32 v39, v39
	v_cvt_pk_bf16_f32 v144, v32, v33
	v_cvt_pk_bf16_f32 v145, v34, v35
	v_cvt_pk_bf16_f32 v146, v36, v37
	v_cvt_pk_bf16_f32 v147, v38, v39
	s_waitcnt lgkmcnt(3)
	v_mfma_f32_32x32x16_bf16 v[16:31], v[140:143], v[144:147], v[16:31]
	v_exp_f32_e32 v40, v40
	s_waitcnt lgkmcnt(2)
	v_mfma_f32_32x32x16_bf16 v[0:15], v[136:139], v[144:147], v[0:15]
	v_exp_f32_e32 v41, v41
	v_exp_f32_e32 v42, v42
	v_exp_f32_e32 v43, v43
	v_exp_f32_e32 v44, v44
	v_exp_f32_e32 v45, v45
	v_exp_f32_e32 v46, v46
	v_exp_f32_e32 v47, v47
	v_cvt_pk_bf16_f32 v136, v40, v41
	v_cvt_pk_bf16_f32 v137, v42, v43
	v_cvt_pk_bf16_f32 v138, v44, v45
	v_cvt_pk_bf16_f32 v139, v46, v47
	s_add_i32 s4, s4, 3
	s_cmp_ge_u32 s4, s13
	s_waitcnt lgkmcnt(1)
	v_mfma_f32_32x32x16_bf16 v[16:31], v[128:131], v[136:139], v[16:31]
	s_waitcnt vmcnt(1)
	ds_write_b128 v194, v[112:115] offset:44032
	ds_write_b128 v204, v[108:111] offset:44032
	ds_write_b128 v206, v[116:119] offset:44032
	ds_write_b64 v208, v[120:121] offset:44032
	ds_write_b64 v208, v[122:123] offset:44048
	s_waitcnt vmcnt(0)
	ds_write_b64 v208, v[124:125] offset:52736
	ds_write_b64 v208, v[126:127] offset:52752
	s_waitcnt lgkmcnt(0)
	s_barrier
	v_mfma_f32_32x32x16_bf16 v[0:15], v[132:135], v[136:139], v[0:15]
	s_cbranch_scc1 .LBB0_803
	v_lshl_add_u64 v[108:109], s[94:95], 0, v[174:175]
	v_add_co_u32_e32 v108, vcc, 0x18b2e000, v108
	v_lshl_add_u64 v[110:111], s[94:95], 0, v[172:173]
	s_nop 0
	v_addc_co_u32_e32 v109, vcc, 0, v109, vcc
	v_add_co_u32_e32 v110, vcc, 0x18b2e000, v110
	v_lshl_add_u64 v[116:117], s[94:95], 0, v[170:171]
	s_nop 0
	v_addc_co_u32_e32 v111, vcc, 0, v111, vcc
	v_add_co_u32_e32 v116, vcc, 0x18b2e000, v116
	v_lshl_add_u64 v[120:121], s[94:95], 0, v[166:167]
	s_nop 0
	v_addc_co_u32_e32 v117, vcc, 0, v117, vcc
	v_lshl_add_u64 v[124:125], s[94:95], 0, v[168:169]
	global_load_dwordx4 v[112:115], v[108:109], off
	s_nop 0
	global_load_dwordx4 v[108:111], v[110:111], off
	s_nop 0
	global_load_dwordx4 v[116:119], v[116:117], off
	s_nop 0
	global_load_dwordx4 v[120:123], v[120:121], off
	s_nop 0
	global_load_dwordx4 v[124:127], v[124:125], off
.LBB0_803:
	v_add_f32_e32 v48, 0, v48
	v_add_f32_e32 v48, v49, v48
	v_add_f32_e32 v48, v50, v48
	v_add_f32_e32 v48, v51, v48
	v_add_f32_e32 v48, v52, v48
	v_add_f32_e32 v48, v53, v48
	v_add_f32_e32 v48, v54, v48
	v_add_f32_e32 v48, v55, v48
	v_add_f32_e32 v48, v56, v48
	v_add_f32_e32 v48, v57, v48
	v_add_f32_e32 v48, v58, v48
	v_add_f32_e32 v48, v59, v48
	v_add_f32_e32 v48, v60, v48
	v_add_f32_e32 v48, v61, v48
	v_add_f32_e32 v48, v62, v48
	v_add_f32_e32 v48, v63, v48
	v_add_f32_e32 v32, v32, v48
	v_add_f32_e32 v32, v33, v32
	v_add_f32_e32 v32, v34, v32
	v_add_f32_e32 v32, v35, v32
	v_add_f32_e32 v32, v36, v32
	v_add_f32_e32 v32, v37, v32
	v_add_f32_e32 v32, v38, v32
	v_add_f32_e32 v32, v39, v32
	v_add_f32_e32 v32, v40, v32
	v_add_f32_e32 v32, v41, v32
	v_add_f32_e32 v32, v42, v32
	v_add_f32_e32 v32, v43, v32
	v_add_f32_e32 v32, v44, v32
	v_add_f32_e32 v32, v45, v32
	v_add_f32_e32 v32, v46, v32
	v_add_f32_e32 v32, v47, v32
	v_add_f32_e32 v213, v213, v32
	ds_read_b128 v[32:35], v210 offset:44032
	ds_read_b128 v[128:131], v210 offset:44064
	ds_read_b128 v[132:135], v210 offset:44096
	ds_read_b128 v[136:139], v210 offset:44128
	ds_read_b128 v[140:143], v210 offset:44160
	ds_read_b128 v[144:147], v210 offset:44192
	ds_read_b128 v[36:39], v210 offset:50688
	ds_read_b128 v[148:151], v210 offset:50720
	ds_read_b128 v[152:155], v210 offset:50752
	ds_read_b128 v[156:159], v210 offset:50784
	ds_read_b128 v[214:217], v210 offset:50816
	ds_read_b128 v[234:237], v210 offset:50848
	s_waitcnt lgkmcnt(11)
	v_mfma_f32_32x32x16_bf16 v[48:63], v[32:35], v[64:67], v[176:191]
	s_waitcnt lgkmcnt(5)
	v_mfma_f32_32x32x16_bf16 v[32:47], v[36:39], v[64:67], v[176:191]
	v_mfma_f32_32x32x16_bf16 v[48:63], v[128:131], v[68:71], v[48:63]
	s_waitcnt lgkmcnt(4)
	v_mfma_f32_32x32x16_bf16 v[32:47], v[148:151], v[68:71], v[32:47]
	v_mfma_f32_32x32x16_bf16 v[48:63], v[132:135], v[72:75], v[48:63]
	s_waitcnt lgkmcnt(3)
	v_mfma_f32_32x32x16_bf16 v[32:47], v[152:155], v[72:75], v[32:47]
	v_mfma_f32_32x32x16_bf16 v[48:63], v[136:139], v[88:91], v[48:63]
	s_waitcnt lgkmcnt(2)
	v_mfma_f32_32x32x16_bf16 v[32:47], v[156:159], v[88:91], v[32:47]
	v_mfma_f32_32x32x16_bf16 v[48:63], v[140:143], v[96:99], v[48:63]
	s_waitcnt lgkmcnt(1)
	v_mfma_f32_32x32x16_bf16 v[32:47], v[214:217], v[96:99], v[32:47]
	v_mfma_f32_32x32x16_bf16 v[48:63], v[144:147], v[100:103], v[48:63]
	s_waitcnt lgkmcnt(0)
	v_mfma_f32_32x32x16_bf16 v[32:47], v[234:237], v[100:103], v[32:47]
	s_nop 3
	ds_read_b128 v[152:155], v211 offset:52736
	ds_read_b128 v[156:159], v211 offset:44032
	ds_read_b128 v[148:151], v211 offset:44064
	ds_read_b128 v[144:147], v211 offset:52768
	ds_read_b128 v[140:143], v211 offset:44096
	ds_read_b128 v[136:139], v211 offset:52800
	ds_read_b128 v[132:135], v211 offset:44128
	ds_read_b128 v[128:131], v211 offset:52832
	v_max_f32_e32 v195, v32, v32
	v_max_f32_e32 v200, v48, v48
	v_max_f32_e32 v195, v200, v195
	v_max3_f32 v195, v195, v49, v33
	v_max3_f32 v195, v195, v50, v34
	v_max3_f32 v195, v195, v51, v35
	v_max3_f32 v195, v195, v52, v36
	v_max3_f32 v195, v195, v53, v37
	v_max3_f32 v195, v195, v54, v38
	v_max3_f32 v195, v195, v55, v39
	v_max3_f32 v195, v195, v56, v40
	v_max3_f32 v195, v195, v57, v41
	v_max3_f32 v195, v195, v58, v42
	v_max3_f32 v195, v195, v59, v43
	v_max3_f32 v195, v195, v60, v44
	v_max3_f32 v195, v195, v61, v45
	v_max3_f32 v195, v195, v62, v46
	v_max3_f32 v215, v195, v63, v47
	v_cmp_gt_f32_e32 vcc, v215, v220
	s_cbranch_vccz .LBB0_805
; #define MFMA(a, b, c) __builtin_amdgcn_mfma_f32_32x32x16_bf16((a), (b), (c), 0, 0, 0)
; DI float fexp2(float x) { return __builtin_amdgcn_exp2f(x); }
; DI void phase_attn(const Params& p, int hf, bool skipctx, char* smem, int& rot) {
;     ...
;       if (__any(mx > m_run + 8.f)) {
;         mx = fmaxf(mx, __shfl_xor(mx, 32));
;         const float m_new = fmaxf(m_run, mx);
;         const float alpha = fexp2(m_run - m_new);
;         m_run = m_new;
;         l_run *= alpha;
; #pragma unroll
;         for (int i = 0; i < 16; ++i) { o[0][i] *= alpha; o[1][i] *= alpha; }
;       }
;       float ps = 0.f;
; #pragma unroll
;       for (int kb = 0; kb < 2; ++kb)
; #pragma unroll
;         for (int i = 0; i < 16; ++i) { const float e = fexp2(st[kb][i] - m_run); st[kb][i] = e; ps += e; }
;       l_run += ps;
; #pragma unroll
;       for (int kb = 0; kb < 2; ++kb)
; #pragma unroll
;         for (int s2 = 0; s2 < 2; ++s2) {
;           const bf16x8 pb = pack8(st[kb][8 * s2 + 0], st[kb][8 * s2 + 1], st[kb][8 * s2 + 2], st[kb][8 * s2 + 3], st[kb][8 * s2 + 4], st[kb][8 * s2 + 5], st[kb][8 * s2 + 6], st[kb][8 * s2 + 7]);
; #pragma unroll
;           for (int dvb = 0; dvb < 2; ++dvb) o[dvb] = MFMA(vf[kb][s2][dvb], pb, o[dvb]);
	v_sub_f32_e32 v215, v215, v176
	v_cmp_lt_i32_e32 vcc, v224, v207
	s_nop 1
	v_cndmask_b32_e32 v195, v205, v224, vcc
	v_lshlrev_b32_e32 v195, 2, v195
	ds_bpermute_b32 v195, v195, v215
	s_waitcnt lgkmcnt(0)
	v_max3_f32 v195, v212, v215, v195
	v_sub_f32_e32 v200, v212, v195
	v_exp_f32_e32 v200, v200
	v_mov_b32_e32 v212, v195
	v_mul_f32_e32 v213, v213, v200
	v_pk_mul_f32 v[30:31], v[30:31], v[200:201] op_sel_hi:[1,0]
	v_pk_mul_f32 v[28:29], v[28:29], v[200:201] op_sel_hi:[1,0]
	v_pk_mul_f32 v[26:27], v[26:27], v[200:201] op_sel_hi:[1,0]
	v_pk_mul_f32 v[24:25], v[24:25], v[200:201] op_sel_hi:[1,0]
	v_pk_mul_f32 v[22:23], v[22:23], v[200:201] op_sel_hi:[1,0]
	v_pk_mul_f32 v[20:21], v[20:21], v[200:201] op_sel_hi:[1,0]
	v_pk_mul_f32 v[18:19], v[18:19], v[200:201] op_sel_hi:[1,0]
	v_pk_mul_f32 v[16:17], v[16:17], v[200:201] op_sel_hi:[1,0]
	v_pk_mul_f32 v[14:15], v[14:15], v[200:201] op_sel_hi:[1,0]
	v_pk_mul_f32 v[12:13], v[12:13], v[200:201] op_sel_hi:[1,0]
	v_pk_mul_f32 v[10:11], v[10:11], v[200:201] op_sel_hi:[1,0]
	v_pk_mul_f32 v[8:9], v[8:9], v[200:201] op_sel_hi:[1,0]
	v_pk_mul_f32 v[6:7], v[6:7], v[200:201] op_sel_hi:[1,0]
	v_pk_mul_f32 v[4:5], v[4:5], v[200:201] op_sel_hi:[1,0]
	v_pk_mul_f32 v[2:3], v[2:3], v[200:201] op_sel_hi:[1,0]
	v_pk_mul_f32 v[0:1], v[0:1], v[200:201] op_sel_hi:[1,0]
	v_add_f32_e32 v202, v195, v176
	v_sub_f32_e32 v32, v32, v202
	v_sub_f32_e32 v33, v33, v202
	v_sub_f32_e32 v34, v34, v202
	v_sub_f32_e32 v35, v35, v202
	v_sub_f32_e32 v36, v36, v202
	v_sub_f32_e32 v37, v37, v202
	v_sub_f32_e32 v38, v38, v202
	v_sub_f32_e32 v39, v39, v202
	v_sub_f32_e32 v40, v40, v202
	v_sub_f32_e32 v41, v41, v202
	v_sub_f32_e32 v42, v42, v202
	v_sub_f32_e32 v43, v43, v202
	v_sub_f32_e32 v44, v44, v202
	v_sub_f32_e32 v45, v45, v202
	v_sub_f32_e32 v46, v46, v202
	v_sub_f32_e32 v47, v47, v202
	v_sub_f32_e32 v48, v48, v202
	v_sub_f32_e32 v49, v49, v202
	v_sub_f32_e32 v50, v50, v202
	v_sub_f32_e32 v51, v51, v202
	v_sub_f32_e32 v52, v52, v202
	v_sub_f32_e32 v53, v53, v202
	v_sub_f32_e32 v54, v54, v202
	v_sub_f32_e32 v55, v55, v202
	v_sub_f32_e32 v56, v56, v202
	v_sub_f32_e32 v57, v57, v202
	v_sub_f32_e32 v58, v58, v202
	v_sub_f32_e32 v59, v59, v202
	v_sub_f32_e32 v60, v60, v202
	v_sub_f32_e32 v61, v61, v202
	v_sub_f32_e32 v62, v62, v202
	v_sub_f32_e32 v63, v63, v202
	v_sub_f32_e32 v176, 0, v195
	v_sub_f32_e32 v177, 0, v195
	v_sub_f32_e32 v178, 0, v195
	v_sub_f32_e32 v179, 0, v195
	v_sub_f32_e32 v180, 0, v195
	v_sub_f32_e32 v181, 0, v195
	v_sub_f32_e32 v182, 0, v195
	v_sub_f32_e32 v183, 0, v195
	v_sub_f32_e32 v184, 0, v195
	v_sub_f32_e32 v185, 0, v195
	v_sub_f32_e32 v186, 0, v195
	v_sub_f32_e32 v187, 0, v195
	v_sub_f32_e32 v188, 0, v195
	v_sub_f32_e32 v189, 0, v195
	v_sub_f32_e32 v190, 0, v195
	v_sub_f32_e32 v191, 0, v195
	v_mov_b32_e32 v220, 0x41000000
.LBB0_805:
	v_exp_f32_e32 v48, v48
	v_exp_f32_e32 v49, v49
	v_exp_f32_e32 v50, v50
	v_exp_f32_e32 v51, v51
	v_add_f32_e32 v195, 0, v48
	v_exp_f32_e32 v52, v52
	v_add_f32_e32 v195, v49, v195
	v_exp_f32_e32 v53, v53
	v_add_f32_e32 v195, v50, v195
	v_exp_f32_e32 v54, v54
	v_add_f32_e32 v195, v51, v195
	v_exp_f32_e32 v55, v55
	v_add_f32_e32 v195, v52, v195
	v_exp_f32_e32 v56, v56
	v_add_f32_e32 v195, v53, v195
	v_exp_f32_e32 v57, v57
	v_add_f32_e32 v195, v54, v195
	v_exp_f32_e32 v58, v58
	v_add_f32_e32 v195, v55, v195
	v_exp_f32_e32 v59, v59
	v_add_f32_e32 v195, v56, v195
	v_exp_f32_e32 v60, v60
	v_add_f32_e32 v195, v57, v195
	v_exp_f32_e32 v61, v61
	v_add_f32_e32 v195, v58, v195
	v_exp_f32_e32 v62, v62
	v_add_f32_e32 v195, v59, v195
	v_exp_f32_e32 v63, v63
	v_add_f32_e32 v195, v60, v195
	v_exp_f32_e32 v200, v32
	v_add_f32_e32 v195, v61, v195
	v_exp_f32_e32 v201, v33
	v_add_f32_e32 v32, v62, v195
	v_exp_f32_e32 v195, v34
	v_add_f32_e32 v32, v63, v32
	v_exp_f32_e32 v202, v35
	v_add_f32_e32 v32, v200, v32
	v_exp_f32_e32 v36, v36
	v_add_f32_e32 v32, v201, v32
	v_exp_f32_e32 v37, v37
	v_add_f32_e32 v32, v195, v32
	v_add_f32_e32 v32, v202, v32
	v_add_f32_e32 v32, v36, v32
	v_add_f32_e32 v203, v37, v32
	v_cvt_pk_bf16_f32 v32, v48, v49
	v_cvt_pk_bf16_f32 v33, v50, v51
	v_cvt_pk_bf16_f32 v34, v52, v53
	v_cvt_pk_bf16_f32 v35, v54, v55
	v_exp_f32_e32 v38, v38
	s_waitcnt lgkmcnt(6)
	v_mfma_f32_32x32x16_bf16 v[16:31], v[156:159], v[32:35], v[16:31]
	v_exp_f32_e32 v39, v39
	v_exp_f32_e32 v40, v40
	v_add_f32_e32 v48, v38, v203
	v_exp_f32_e32 v42, v42
	v_mfma_f32_32x32x16_bf16 v[0:15], v[152:155], v[32:35], v[0:15]
	v_exp_f32_e32 v41, v41
	v_cvt_pk_bf16_f32 v32, v56, v57
	v_cvt_pk_bf16_f32 v33, v58, v59
	v_cvt_pk_bf16_f32 v34, v60, v61
	v_cvt_pk_bf16_f32 v35, v62, v63
	v_add_f32_e32 v48, v39, v48
	s_waitcnt lgkmcnt(5)
	v_mfma_f32_32x32x16_bf16 v[16:31], v[148:151], v[32:35], v[16:31]
	v_exp_f32_e32 v43, v43
	v_add_f32_e32 v48, v40, v48
	v_exp_f32_e32 v44, v44
	v_add_f32_e32 v48, v41, v48
	s_waitcnt lgkmcnt(4)
	v_mfma_f32_32x32x16_bf16 v[0:15], v[144:147], v[32:35], v[0:15]
	v_add_f32_e32 v32, v42, v48
	v_add_f32_e32 v32, v43, v32
	v_add_f32_e32 v48, v44, v32
	v_cvt_pk_bf16_f32 v32, v200, v201
	v_cvt_pk_bf16_f32 v33, v195, v202
	v_cvt_pk_bf16_f32 v34, v36, v37
	v_cvt_pk_bf16_f32 v35, v38, v39
	v_exp_f32_e32 v36, v45
	s_waitcnt lgkmcnt(3)
	v_mfma_f32_32x32x16_bf16 v[16:31], v[140:143], v[32:35], v[16:31]
	v_exp_f32_e32 v37, v46
	v_exp_f32_e32 v38, v47
	v_add_f32_e32 v39, v36, v48
	s_waitcnt lgkmcnt(2)
	v_mfma_f32_32x32x16_bf16 v[0:15], v[136:139], v[32:35], v[0:15]
	v_add_f32_e32 v32, v37, v39
	v_add_f32_e32 v32, v38, v32
	v_add_f32_e32 v213, v213, v32
	v_cvt_pk_bf16_f32 v32, v40, v41
	v_cvt_pk_bf16_f32 v33, v42, v43
	v_cvt_pk_bf16_f32 v34, v44, v36
	v_cvt_pk_bf16_f32 v35, v37, v38
	s_waitcnt lgkmcnt(1)
; #define MFMA(a, b, c) __builtin_amdgcn_mfma_f32_32x32x16_bf16((a), (b), (c), 0, 0, 0)
; DI float fexp2(float x) { return __builtin_amdgcn_exp2f(x); }
; DI void phase_attn(const Params& p, int hf, bool skipctx, char* smem, int& rot) {
;     ...
;         bf16x8 kf[2][6];
; #pragma unroll
;         for (int kb = 0; kb < 2; ++kb)
; #pragma unroll
;           for (int ks = 0; ks < 6; ++ks) kf[kb][ks] = *(const bf16x8*)(sk + (kb * 32 + r) * KROW + (ks * 16 + h * 8) * 2);
;         __builtin_amdgcn_sched_barrier(0);
; #pragma unroll
;         for (int ks = 0; ks < 6; ++ks)
; #pragma unroll
;           for (int kb = 0; kb < 2; ++kb) st[kb] = MFMA(kf[kb][ks], qf[ks], st[kb]);
;         __builtin_amdgcn_sched_barrier(0);
;       }
;       bf16x8 vf[2][2][2];
; #pragma unroll
;       for (int kb = 0; kb < 2; ++kb)
; #pragma unroll
;         for (int s2 = 0; s2 < 2; ++s2)
; #pragma unroll
;           for (int dvb = 0; dvb < 2; ++dvb) {
;             const char* vp = sv + (dvb * 32 + r) * VROW + (kb * 32 + 16 * s2 + 4 * h) * 2;
;             const s16x4 lo = *(const s16x4*)vp, hi = *(const s16x4*)(vp + 16);
;             vf[kb][s2][dvb] = __builtin_shufflevector(lo, hi, 0, 1, 2, 3, 4, 5, 6, 7);
;           }
;       float mx = st[0][0];
; #pragma unroll
;       for (int i = 0; i < 16; ++i) { mx = fmaxf(mx, st[0][i]); mx = fmaxf(mx, st[1][i]); }
;       if (__any(mx > m_run + 8.f)) {
;         mx = fmaxf(mx, __shfl_xor(mx, 32));
;         const float m_new = fmaxf(m_run, mx);
;         const float alpha = fexp2(m_run - m_new);
;         m_run = m_new;
;         l_run *= alpha;
; #pragma unroll
;         for (int i = 0; i < 16; ++i) { o[0][i] *= alpha; o[1][i] *= alpha; }
;       }
	s_nop 0
	v_mfma_f32_32x32x16_bf16 v[16:31], v[132:135], v[32:35], v[16:31]
	ds_read_b128 v[36:39], v210 offset:57344
	ds_read_b128 v[132:135], v210 offset:57376
	ds_read_b128 v[136:139], v210 offset:57408
	ds_read_b128 v[140:143], v210 offset:57440
	ds_read_b128 v[144:147], v210 offset:57472
	ds_read_b128 v[148:151], v210 offset:57504
	ds_read_b128 v[40:43], v210 offset:64000
	ds_read_b128 v[152:155], v210 offset:64032
	ds_read_b128 v[156:159], v210 offset:64064
	ds_read_b128 v[216:219], v210 offset:64096
	ds_read_b128 v[234:237], v210 offset:64128
	ds_read_b128 v[238:241], v210 offset:64160
	s_waitcnt lgkmcnt(12)
	v_mfma_f32_32x32x16_bf16 v[0:15], v[128:131], v[32:35], v[0:15]
	s_waitcnt lgkmcnt(11)
	v_mfma_f32_32x32x16_bf16 v[48:63], v[36:39], v[64:67], v[176:191]
	s_waitcnt lgkmcnt(5)
	v_mfma_f32_32x32x16_bf16 v[32:47], v[40:43], v[64:67], v[176:191]
	v_mfma_f32_32x32x16_bf16 v[48:63], v[132:135], v[68:71], v[48:63]
	s_waitcnt lgkmcnt(4)
	v_mfma_f32_32x32x16_bf16 v[32:47], v[152:155], v[68:71], v[32:47]
	v_mfma_f32_32x32x16_bf16 v[48:63], v[136:139], v[72:75], v[48:63]
	s_waitcnt lgkmcnt(3)
	v_mfma_f32_32x32x16_bf16 v[32:47], v[156:159], v[72:75], v[32:47]
	v_mfma_f32_32x32x16_bf16 v[48:63], v[140:143], v[88:91], v[48:63]
	s_waitcnt lgkmcnt(2)
	v_mfma_f32_32x32x16_bf16 v[32:47], v[216:219], v[88:91], v[32:47]
	v_mfma_f32_32x32x16_bf16 v[48:63], v[144:147], v[96:99], v[48:63]
	s_waitcnt lgkmcnt(1)
	v_mfma_f32_32x32x16_bf16 v[32:47], v[234:237], v[96:99], v[32:47]
	v_mfma_f32_32x32x16_bf16 v[48:63], v[148:151], v[100:103], v[48:63]
	s_waitcnt lgkmcnt(0)
	v_mfma_f32_32x32x16_bf16 v[32:47], v[238:241], v[100:103], v[32:47]
	s_nop 3
	ds_read_b128 v[152:155], v211 offset:52864
	ds_read_b128 v[156:159], v211 offset:44160
	ds_read_b128 v[148:151], v211 offset:44192
	ds_read_b128 v[144:147], v211 offset:52896
	ds_read_b128 v[140:143], v211 offset:44224
	ds_read_b128 v[136:139], v211 offset:52928
	ds_read_b128 v[132:135], v211 offset:44256
	ds_read_b128 v[128:131], v211 offset:52960
	v_max_f32_e32 v195, v32, v32
	v_max_f32_e32 v200, v48, v48
	v_max_f32_e32 v195, v200, v195
	v_max3_f32 v195, v195, v49, v33
	v_max3_f32 v195, v195, v50, v34
	v_max3_f32 v195, v195, v51, v35
	v_max3_f32 v195, v195, v52, v36
	v_max3_f32 v195, v195, v53, v37
	v_max3_f32 v195, v195, v54, v38
	v_max3_f32 v195, v195, v55, v39
	v_max3_f32 v195, v195, v56, v40
	v_max3_f32 v195, v195, v57, v41
	v_max3_f32 v195, v195, v58, v42
	v_max3_f32 v195, v195, v59, v43
	v_max3_f32 v195, v195, v60, v44
	v_max3_f32 v195, v195, v61, v45
	v_max3_f32 v195, v195, v62, v46
	v_max3_f32 v215, v195, v63, v47
	v_cmp_gt_f32_e32 vcc, v215, v220
	s_cbranch_vccz .LBB0_807
	v_sub_f32_e32 v215, v215, v176
	v_cmp_lt_i32_e32 vcc, v224, v207
	s_nop 1
	v_cndmask_b32_e32 v195, v205, v224, vcc
	v_lshlrev_b32_e32 v195, 2, v195
	ds_bpermute_b32 v195, v195, v215
	s_waitcnt lgkmcnt(0)
	v_max3_f32 v195, v212, v215, v195
	v_sub_f32_e32 v200, v212, v195
	v_exp_f32_e32 v200, v200
	v_mov_b32_e32 v212, v195
	v_mul_f32_e32 v213, v213, v200
	v_pk_mul_f32 v[30:31], v[30:31], v[200:201] op_sel_hi:[1,0]
	v_pk_mul_f32 v[28:29], v[28:29], v[200:201] op_sel_hi:[1,0]
	v_pk_mul_f32 v[26:27], v[26:27], v[200:201] op_sel_hi:[1,0]
	v_pk_mul_f32 v[24:25], v[24:25], v[200:201] op_sel_hi:[1,0]
	v_pk_mul_f32 v[22:23], v[22:23], v[200:201] op_sel_hi:[1,0]
	v_pk_mul_f32 v[20:21], v[20:21], v[200:201] op_sel_hi:[1,0]
	v_pk_mul_f32 v[18:19], v[18:19], v[200:201] op_sel_hi:[1,0]
	v_pk_mul_f32 v[16:17], v[16:17], v[200:201] op_sel_hi:[1,0]
	v_pk_mul_f32 v[14:15], v[14:15], v[200:201] op_sel_hi:[1,0]
	v_pk_mul_f32 v[12:13], v[12:13], v[200:201] op_sel_hi:[1,0]
	v_pk_mul_f32 v[10:11], v[10:11], v[200:201] op_sel_hi:[1,0]
	v_pk_mul_f32 v[8:9], v[8:9], v[200:201] op_sel_hi:[1,0]
	v_pk_mul_f32 v[6:7], v[6:7], v[200:201] op_sel_hi:[1,0]
	v_pk_mul_f32 v[4:5], v[4:5], v[200:201] op_sel_hi:[1,0]
	v_pk_mul_f32 v[2:3], v[2:3], v[200:201] op_sel_hi:[1,0]
	v_pk_mul_f32 v[0:1], v[0:1], v[200:201] op_sel_hi:[1,0]
	v_add_f32_e32 v202, v195, v176
	v_sub_f32_e32 v32, v32, v202
	v_sub_f32_e32 v33, v33, v202
	v_sub_f32_e32 v34, v34, v202
	v_sub_f32_e32 v35, v35, v202
	v_sub_f32_e32 v36, v36, v202
	v_sub_f32_e32 v37, v37, v202
	v_sub_f32_e32 v38, v38, v202
	v_sub_f32_e32 v39, v39, v202
	v_sub_f32_e32 v40, v40, v202
	v_sub_f32_e32 v41, v41, v202
	v_sub_f32_e32 v42, v42, v202
	v_sub_f32_e32 v43, v43, v202
	v_sub_f32_e32 v44, v44, v202
	v_sub_f32_e32 v45, v45, v202
	v_sub_f32_e32 v46, v46, v202
	v_sub_f32_e32 v47, v47, v202
	v_sub_f32_e32 v48, v48, v202
	v_sub_f32_e32 v49, v49, v202
	v_sub_f32_e32 v50, v50, v202
	v_sub_f32_e32 v51, v51, v202
	v_sub_f32_e32 v52, v52, v202
	v_sub_f32_e32 v53, v53, v202
	v_sub_f32_e32 v54, v54, v202
	v_sub_f32_e32 v55, v55, v202
	v_sub_f32_e32 v56, v56, v202
	v_sub_f32_e32 v57, v57, v202
	v_sub_f32_e32 v58, v58, v202
	v_sub_f32_e32 v59, v59, v202
	v_sub_f32_e32 v60, v60, v202
	v_sub_f32_e32 v61, v61, v202
	v_sub_f32_e32 v62, v62, v202
	v_sub_f32_e32 v63, v63, v202
	v_sub_f32_e32 v176, 0, v195
	v_sub_f32_e32 v177, 0, v195
	v_sub_f32_e32 v178, 0, v195
	v_sub_f32_e32 v179, 0, v195
	v_sub_f32_e32 v180, 0, v195
	v_sub_f32_e32 v181, 0, v195
	v_sub_f32_e32 v182, 0, v195
	v_sub_f32_e32 v183, 0, v195
	v_sub_f32_e32 v184, 0, v195
	v_sub_f32_e32 v185, 0, v195
	v_sub_f32_e32 v186, 0, v195
	v_sub_f32_e32 v187, 0, v195
	v_sub_f32_e32 v188, 0, v195
	v_sub_f32_e32 v189, 0, v195
	v_sub_f32_e32 v190, 0, v195
	v_sub_f32_e32 v191, 0, v195
	v_mov_b32_e32 v220, 0x41000000
; #define MFMA(a, b, c) __builtin_amdgcn_mfma_f32_32x32x16_bf16((a), (b), (c), 0, 0, 0)
; DI float fexp2(float x) { return __builtin_amdgcn_exp2f(x); }
; DI void phase_attn(const Params& p, int hf, bool skipctx, char* smem, int& rot) {
;     ...
;       float ps = 0.f;
; #pragma unroll
;       for (int kb = 0; kb < 2; ++kb)
; #pragma unroll
;         for (int i = 0; i < 16; ++i) { const float e = fexp2(st[kb][i] - m_run); st[kb][i] = e; ps += e; }
;       l_run += ps;
; #pragma unroll
;       for (int kb = 0; kb < 2; ++kb)
; #pragma unroll
;         for (int s2 = 0; s2 < 2; ++s2) {
;           const bf16x8 pb = pack8(st[kb][8 * s2 + 0], st[kb][8 * s2 + 1], st[kb][8 * s2 + 2], st[kb][8 * s2 + 3], st[kb][8 * s2 + 4], st[kb][8 * s2 + 5], st[kb][8 * s2 + 6], st[kb][8 * s2 + 7]);
; #pragma unroll
;           for (int dvb = 0; dvb < 2; ++dvb) o[dvb] = MFMA(vf[kb][s2][dvb], pb, o[dvb]);
;         }
;     };
;     __syncthreads();
;     ATT_LOAD(ak0, ak1, ak2, av0, av1, 0);
;     ATT_LOAD(bk0, bk1, bk2, bv0, bv1, 1);
;     ATT_WRITE(ak0, ak1, ak2, av0, av1, 0);
;     __syncthreads();
;     for (int kt = 0; kt < nkt; kt += 2) {
;       if (kt + 2 < nkt) ATT_LOAD(ak0, ak1, ak2, av0, av1, kt + 2);
;       compute(0, 0); compute(0, 1);
;       ATT_WRITE(bk0, bk1, bk2, bv0, bv1, 1);
;       __syncthreads();
;       if (kt + 3 < nkt) ATT_LOAD(bk0, bk1, bk2, bv0, bv1, kt + 3);
;       compute(1, 0); compute(1, 1);
;       if (kt + 2 < nkt) ATT_WRITE(ak0, ak1, ak2, av0, av1, 0);
.LBB0_807:
	v_exp_f32_e32 v48, v48
	v_exp_f32_e32 v49, v49
	v_exp_f32_e32 v50, v50
	v_exp_f32_e32 v51, v51
	v_exp_f32_e32 v52, v52
	v_exp_f32_e32 v53, v53
	v_exp_f32_e32 v54, v54
	v_exp_f32_e32 v55, v55
	v_cvt_pk_bf16_f32 v214, v48, v49
	v_cvt_pk_bf16_f32 v215, v50, v51
	v_cvt_pk_bf16_f32 v216, v52, v53
	v_cvt_pk_bf16_f32 v217, v54, v55
	s_waitcnt lgkmcnt(6)
	v_mfma_f32_32x32x16_bf16 v[16:31], v[156:159], v[214:217], v[16:31]
	v_exp_f32_e32 v56, v56
	v_mfma_f32_32x32x16_bf16 v[0:15], v[152:155], v[214:217], v[0:15]
	v_exp_f32_e32 v57, v57
	v_exp_f32_e32 v58, v58
	v_exp_f32_e32 v59, v59
	v_exp_f32_e32 v60, v60
	v_exp_f32_e32 v61, v61
	v_exp_f32_e32 v62, v62
	v_exp_f32_e32 v63, v63
	v_cvt_pk_bf16_f32 v152, v56, v57
	v_cvt_pk_bf16_f32 v153, v58, v59
	v_cvt_pk_bf16_f32 v154, v60, v61
	v_cvt_pk_bf16_f32 v155, v62, v63
	s_waitcnt lgkmcnt(5)
	v_mfma_f32_32x32x16_bf16 v[16:31], v[148:151], v[152:155], v[16:31]
	v_exp_f32_e32 v32, v32
	s_waitcnt lgkmcnt(4)
	v_mfma_f32_32x32x16_bf16 v[0:15], v[144:147], v[152:155], v[0:15]
	v_exp_f32_e32 v33, v33
	v_exp_f32_e32 v34, v34
	v_exp_f32_e32 v35, v35
	v_exp_f32_e32 v36, v36
	v_exp_f32_e32 v37, v37
	v_exp_f32_e32 v38, v38
	v_exp_f32_e32 v39, v39
	v_cvt_pk_bf16_f32 v144, v32, v33
	v_cvt_pk_bf16_f32 v145, v34, v35
	v_cvt_pk_bf16_f32 v146, v36, v37
	v_cvt_pk_bf16_f32 v147, v38, v39
	s_waitcnt lgkmcnt(3)
	v_mfma_f32_32x32x16_bf16 v[16:31], v[140:143], v[144:147], v[16:31]
	v_exp_f32_e32 v40, v40
	s_waitcnt lgkmcnt(2)
	v_mfma_f32_32x32x16_bf16 v[0:15], v[136:139], v[144:147], v[0:15]
	v_exp_f32_e32 v41, v41
	v_exp_f32_e32 v42, v42
	v_exp_f32_e32 v43, v43
	v_exp_f32_e32 v44, v44
	v_exp_f32_e32 v45, v45
	v_exp_f32_e32 v46, v46
	v_exp_f32_e32 v47, v47
	v_cvt_pk_bf16_f32 v136, v40, v41
	v_cvt_pk_bf16_f32 v137, v42, v43
	v_cvt_pk_bf16_f32 v138, v44, v45
	v_cvt_pk_bf16_f32 v139, v46, v47
	s_andn2_b64 vcc, exec, s[36:37]
	s_waitcnt lgkmcnt(1)
	v_mfma_f32_32x32x16_bf16 v[16:31], v[132:135], v[136:139], v[16:31]
	s_waitcnt lgkmcnt(0)
	v_mfma_f32_32x32x16_bf16 v[0:15], v[128:131], v[136:139], v[0:15]
	s_cbranch_vccnz .LBB0_809
	ds_write_b128 v194, v[76:79]
	ds_write_b128 v204, v[80:83]
	ds_write_b128 v206, v[84:87]
	ds_write_b64 v208, v[92:93] offset:0
	ds_write_b64 v208, v[94:95] offset:16
	ds_write_b64 v208, v[104:105] offset:8704
	ds_write_b64 v208, v[106:107] offset:8720

; DI float bflo(unsigned u) { return __uint_as_float(u << 16); }
; DI float bfhi(unsigned u) { return __uint_as_float(u & 0xffff0000u); }
; DI f32x16 zero16() { f32x16 z; for (int i = 0; i < 16; ++i) z[i] = 0.f; return z; }
; DI void phase_attn(const Params& p, int hf, bool skipctx, char* smem, int& rot) {
;     ...
;       uint4 qu[6];
; #pragma unroll
;       for (int ks = 0; ks < 6; ++ks) qu[ks] = *(const uint4*)(Qb + tq * 768 + head * 96 + ks * 16 + h * 8);
; #pragma unroll
;       for (int ks = 0; ks < 4; ++ks) {
;         const uint4 u = qu[ks];
;         qf[ks] = pack8(bflo(u.x) * QSCALE, bfhi(u.x) * QSCALE, bflo(u.y) * QSCALE, bfhi(u.y) * QSCALE, bflo(u.z) * QSCALE, bfhi(u.z) * QSCALE, bflo(u.w) * QSCALE, bfhi(u.w) * QSCALE);
;       }
;       const unsigned a1[4] = {qu[4].x, qu[4].y, qu[4].z, qu[4].w}, a2[4] = {qu[5].x, qu[5].y, qu[5].z, qu[5].w};
;       float o1[8], o2[8];
;       const int sq_ = s0 + w * 32 + r;
; #pragma unroll
;       for (int e = 0; e < 8; ++e) {
;         const float x1 = ((e & 1) ? bfhi(a1[e >> 1]) : bflo(a1[e >> 1])) * QSCALE;
;         const float x2 = ((e & 1) ? bfhi(a2[e >> 1]) : bflo(a2[e >> 1])) * QSCALE;
;         float cs = 1.f, sn = 0.f;
;         if (sq_ >= LC) { cs = axc[(sq_ - LC) * 16 + 8 * h + e]; sn = axs[(sq_ - LC) * 16 + 8 * h + e]; }
;         o1[e] = x1 * cs - x2 * sn; o2[e] = x1 * sn + x2 * cs;
;       }
;       qf[4] = pack8(o1[0], o1[1], o1[2], o1[3], o1[4], o1[5], o1[6], o1[7]);
;       qf[5] = pack8(o2[0], o2[1], o2[2], o2[3], o2[4], o2[5], o2[6], o2[7]);
;     }
;     const bf16_t* Kg = Kb + (size_t)(bl * 8 + head) * S * 96;
;     const bf16_t* Vg = VTb + (size_t)(bl * 8 + head) * 64 * S;
;     f32x16 o[2]; o[0] = zero16(); o[1] = zero16();
;     float m_run = -1e30f, l_run = 0.f;
;     uint4 ak0, ak1, ak2, av0, av1, bk0, bk1, bk2, bv0, bv1;
;     const int kr0 = tid / 12, kc0 = tid - kr0 * 12, kr1 = (tid + 512) / 12, kc1 = (tid + 512) - kr1 * 12, kr2 = (tid + 1024) / 12, kc2 = (tid + 1024) - kr2 * 12;
.LBB0_1059:
	s_or_b64 exec, exec, s[26:27]
	s_waitcnt vmcnt(0)
	v_lshlrev_b32_e32 v27, 16, v23
	v_lshlrev_b32_e32 v26, 16, v19
	v_pk_mul_f32 v[26:27], v[26:27], s[48:49] op_sel_hi:[1,0]
	v_lshlrev_b32_e32 v47, 16, v22
	v_pk_mul_f32 v[28:29], v[26:27], v[30:31] op_sel:[0,1] op_sel_hi:[1,0]
	v_pk_mul_f32 v[26:27], v[26:27], v[30:31]
	v_and_b32_e32 v30, 0xffff0000, v19
	v_lshlrev_b32_e32 v46, 16, v18
	v_and_b32_e32 v19, 0xffff0000, v22
	v_and_b32_e32 v18, 0xffff0000, v18
	v_and_b32_e32 v31, 0xffff0000, v23
	v_pk_mul_f32 v[46:47], v[46:47], s[48:49] op_sel_hi:[1,0]
	v_pk_mul_f32 v[22:23], v[18:19], s[48:49] op_sel_hi:[1,0]
	v_pk_mul_f32 v[48:49], v[46:47], v[42:43] op_sel:[0,1] op_sel_hi:[1,0]
	v_pk_mul_f32 v[42:43], v[46:47], v[42:43]
	v_pk_mul_f32 v[18:19], v[22:23], v[40:41] op_sel:[0,1] op_sel_hi:[1,0]
	v_pk_mul_f32 v[22:23], v[22:23], v[40:41]
	v_mov_b32_e32 v40, v42
	v_mov_b32_e32 v41, v22
	v_mov_b32_e32 v22, v43
	v_pk_add_f32 v[22:23], v[40:41], v[22:23]
	v_lshlrev_b32_e32 v41, 16, v21
	v_lshlrev_b32_e32 v40, 16, v17
	v_pk_mul_f32 v[40:41], v[40:41], s[48:49] op_sel_hi:[1,0]
	v_mov_b32_e32 v46, v48
	v_mov_b32_e32 v47, v18
	v_mov_b32_e32 v18, v49
	v_pk_mul_f32 v[42:43], v[40:41], v[32:33] op_sel:[0,1] op_sel_hi:[1,0]
	v_pk_mul_f32 v[40:41], v[40:41], v[32:33]
	v_and_b32_e32 v33, 0xffff0000, v21
	v_and_b32_e32 v32, 0xffff0000, v17
	v_pk_add_f32 v[18:19], v[46:47], v[18:19] neg_lo:[0,1] neg_hi:[0,1]
	v_pk_mul_f32 v[46:47], v[32:33], s[48:49] op_sel_hi:[1,0]
	v_mov_b32_e32 v48, v42
	v_pk_mul_f32 v[32:33], v[46:47], v[34:35] op_sel:[0,1] op_sel_hi:[1,0]
	v_pk_mul_f32 v[34:35], v[46:47], v[34:35]
	v_mov_b32_e32 v49, v32
	v_mov_b32_e32 v32, v43
	v_mov_b32_e32 v42, v40
	v_mov_b32_e32 v43, v34
	v_mov_b32_e32 v34, v41
	v_lshlrev_b32_e32 v41, 16, v20
	v_lshlrev_b32_e32 v40, 16, v16
	v_and_b32_e32 v17, 0xffff0000, v20
	v_and_b32_e32 v16, 0xffff0000, v16
	v_pk_mul_f32 v[40:41], v[40:41], s[48:49] op_sel_hi:[1,0]
	v_pk_mul_f32 v[20:21], v[16:17], s[48:49] op_sel_hi:[1,0]
	v_pk_add_f32 v[34:35], v[42:43], v[34:35]
	v_pk_mul_f32 v[42:43], v[40:41], v[38:39] op_sel:[0,1] op_sel_hi:[1,0]
	v_pk_mul_f32 v[38:39], v[40:41], v[38:39]
	v_pk_mul_f32 v[16:17], v[20:21], v[36:37] op_sel:[0,1] op_sel_hi:[1,0]
	v_pk_mul_f32 v[20:21], v[20:21], v[36:37]
	v_mov_b32_e32 v36, v38
	v_mov_b32_e32 v37, v20
	v_mov_b32_e32 v20, v39
	v_pk_add_f32 v[20:21], v[36:37], v[20:21]
	v_lshlrev_b32_e32 v36, 16, v12
	v_and_b32_e32 v37, 0xffff0000, v12
	v_lshlrev_b32_e32 v12, 16, v13
	v_and_b32_e32 v13, 0xffff0000, v13
	v_pk_mul_f32 v[12:13], v[12:13], s[48:49] op_sel_hi:[1,0]
	v_lshlrev_b32_e32 v38, 16, v14
	v_cvt_pk_bf16_f32 v65, v12, v13
	v_lshlrev_b32_e32 v12, 16, v8
	v_and_b32_e32 v13, 0xffff0000, v8
	v_lshlrev_b32_e32 v8, 16, v9
	v_and_b32_e32 v9, 0xffff0000, v9
	v_pk_mul_f32 v[8:9], v[8:9], s[48:49] op_sel_hi:[1,0]
	v_and_b32_e32 v39, 0xffff0000, v14
	v_cvt_pk_bf16_f32 v69, v8, v9
	v_lshlrev_b32_e32 v8, 16, v4
	v_and_b32_e32 v9, 0xffff0000, v4
	v_lshlrev_b32_e32 v4, 16, v5
	v_and_b32_e32 v5, 0xffff0000, v5
	v_lshlrev_b32_e32 v14, 16, v15
	v_and_b32_e32 v15, 0xffff0000, v15
	v_pk_mul_f32 v[4:5], v[4:5], s[48:49] op_sel_hi:[1,0]
	s_mov_b32 s29, 0x2aaaaaab
	v_pk_mul_f32 v[14:15], v[14:15], s[48:49] op_sel_hi:[1,0]
	v_cvt_pk_bf16_f32 v73, v4, v5
	v_mul_hi_i32 v4, v160, s29
	v_cvt_pk_bf16_f32 v67, v14, v15
	v_lshlrev_b32_e32 v14, 16, v10
	v_and_b32_e32 v15, 0xffff0000, v10
	v_lshlrev_b32_e32 v10, 16, v11
	v_and_b32_e32 v11, 0xffff0000, v11
	v_lshrrev_b32_e32 v5, 31, v4
	v_ashrrev_i32_e32 v4, 1, v4
	v_pk_mul_f32 v[10:11], v[10:11], s[48:49] op_sel_hi:[1,0]
	v_add_u32_e32 v45, v4, v5
	v_cvt_pk_bf16_f32 v71, v10, v11
	v_lshlrev_b32_e32 v10, 16, v6
	v_and_b32_e32 v11, 0xffff0000, v6
	v_lshlrev_b32_e32 v6, 16, v7
	v_and_b32_e32 v7, 0xffff0000, v7
	v_mad_u64_u32 v[4:5], s[38:39], v45, -12, v[160:161]
	v_add_u32_e32 v164, 0x200, v160
	v_pk_mul_f32 v[6:7], v[6:7], s[48:49] op_sel_hi:[1,0]
	v_mul_hi_i32 v5, v164, s29
	v_cvt_pk_bf16_f32 v75, v6, v7
	v_lshrrev_b32_e32 v6, 31, v5
	v_ashrrev_i32_e32 v5, 1, v5
	s_mul_i32 s15, s4, 0xcc000
	v_add_u32_e32 v5, v5, v6
	v_pk_mul_f32 v[38:39], v[38:39], s[48:49] op_sel_hi:[1,0]
	v_pk_mul_f32 v[14:15], v[14:15], s[48:49] op_sel_hi:[1,0]
	s_mul_hi_i32 s5, s4, 0xcc000
	s_add_u32 s26, s90, s15
	v_mad_u64_u32 v[6:7], s[38:39], v5, -12, v[164:165]
	v_add_u32_e32 v162, 0x400, v160
	v_cvt_pk_bf16_f32 v66, v38, v39
	v_cvt_pk_bf16_f32 v70, v14, v15
	v_pk_mul_f32 v[8:9], v[8:9], s[48:49] op_sel_hi:[1,0]
	v_pk_mul_f32 v[10:11], v[10:11], s[48:49] op_sel_hi:[1,0]
	s_addc_u32 s27, s91, s5
	v_mul_hi_i32 v7, v162, s29
	v_lshlrev_b32_e32 v14, 3, v4
	v_lshlrev_b32_e32 v38, 3, v6
	v_pk_mul_f32 v[36:37], v[36:37], s[48:49] op_sel_hi:[1,0]
	v_pk_mul_f32 v[12:13], v[12:13], s[48:49] op_sel_hi:[1,0]
	v_cvt_pk_bf16_f32 v72, v8, v9
	v_cvt_pk_bf16_f32 v74, v10, v11
	v_lshrrev_b32_e32 v8, 31, v7
	v_ashrrev_i32_e32 v7, 1, v7
	v_mov_b64_e32 v[10:11], s[26:27]
	v_ashrrev_i32_e32 v15, 31, v14
	v_ashrrev_i32_e32 v39, 31, v38
	v_cvt_pk_bf16_f32 v64, v36, v37
	v_cvt_pk_bf16_f32 v68, v12, v13
	v_add_u32_e32 v7, v7, v8
	v_mad_i64_i32 v[12:13], s[26:27], v45, s17, v[10:11]
	v_lshlrev_b64 v[14:15], 1, v[14:15]
	v_mad_i64_i32 v[36:37], s[26:27], v5, s17, v[10:11]
	v_lshlrev_b64 v[38:39], 1, v[38:39]
	v_mad_u64_u32 v[8:9], s[38:39], v7, -12, v[162:163]
	v_lshl_add_u64 v[12:13], v[12:13], 0, v[14:15]
	v_lshl_add_u64 v[36:37], v[36:37], 0, v[38:39]
	s_barrier
; DI f32x16 zero16() { f32x16 z; for (int i = 0; i < 16; ++i) z[i] = 0.f; return z; }
; DI void phase_attn(const Params& p, int hf, bool skipctx, char* smem, int& rot) {
;     ...
;     const bf16_t* Kg = Kb + (size_t)(bl * 8 + head) * S * 96;
;     const bf16_t* Vg = VTb + (size_t)(bl * 8 + head) * 64 * S;
;     f32x16 o[2]; o[0] = zero16(); o[1] = zero16();
;     float m_run = -1e30f, l_run = 0.f;
;     uint4 ak0, ak1, ak2, av0, av1, bk0, bk1, bk2, bv0, bv1;
;     const int kr0 = tid / 12, kc0 = tid - kr0 * 12, kr1 = (tid + 512) / 12, kc1 = (tid + 512) - kr1 * 12, kr2 = (tid + 1024) / 12, kc2 = (tid + 1024) - kr2 * 12;
;     const int vr0 = tid >> 4, vr1 = (tid + 512) >> 4, vc = tid & 15;
;     ...
;     __syncthreads();
;     ATT_LOAD(ak0, ak1, ak2, av0, av1, 0);
;     ATT_LOAD(bk0, bk1, bk2, bv0, bv1, 1);
	global_load_dwordx4 v[76:79], v[12:13], off
	global_load_dwordx4 v[80:83], v[36:37], off
	v_lshlrev_b32_e32 v36, 3, v8
	s_mul_i32 s15, s4, 0x88000
	v_readlane_b32 s36, v252, 5
	v_ashrrev_i32_e32 v37, 31, v36
	s_mul_hi_i32 s5, s4, 0x88000
	v_readlane_b32 s37, v252, 6
	s_add_u32 s36, s36, s15
	v_mad_i64_i32 v[12:13], s[26:27], v7, s17, v[10:11]
	v_lshlrev_b64 v[36:37], 1, v[36:37]
	s_addc_u32 s37, s37, s5
	v_lshl_add_u64 v[12:13], v[12:13], 0, v[36:37]
	v_mov_b32_e32 v40, v42
	v_mov_b32_e32 v41, v16
	v_mov_b32_e32 v16, v43
	v_ashrrev_i32_e32 v9, 4, v160
	v_ashrrev_i32_e32 v50, 4, v164
	global_load_dwordx4 v[84:87], v[12:13], off
	v_mov_b64_e32 v[12:13], s[36:37]
	v_lshlrev_b32_e32 v165, 4, v160
	v_cvt_pk_bf16_f32 v100, v20, v21
	v_add_u32_e32 v20, 0x80, v5
	v_pk_add_f32 v[16:17], v[40:41], v[16:17] neg_lo:[0,1] neg_hi:[0,1]
	v_mad_i64_i32 v[40:41], s[26:27], v9, s16, v[12:13]
	v_and_b32_e32 v42, 0xf0, v165
	v_mov_b32_e32 v43, v221
	v_mad_i64_i32 v[12:13], s[26:27], v50, s16, v[12:13]
	v_cvt_pk_bf16_f32 v98, v18, v19
	v_cvt_pk_bf16_f32 v102, v22, v23
	v_add_u32_e32 v18, 0x80, v45
	v_mad_i64_i32 v[20:21], s[26:27], v20, s17, v[10:11]
	v_add_u32_e32 v22, 0x80, v7
	v_lshl_add_u64 v[40:41], v[40:41], 0, v[42:43]
	v_lshl_add_u64 v[12:13], v[12:13], 0, v[42:43]
	v_mad_i64_i32 v[18:19], s[26:27], v18, s17, v[10:11]
	v_lshl_add_u64 v[20:21], v[20:21], 0, v[38:39]
	v_mad_i64_i32 v[10:11], s[26:27], v22, s17, v[10:11]
	global_load_dwordx4 v[92:95], v[40:41], off
	global_load_dwordx4 v[104:107], v[12:13], off
	v_lshl_add_u64 v[18:19], v[18:19], 0, v[14:15]
	v_lshl_add_u64 v[10:11], v[10:11], 0, v[36:37]
	global_load_dwordx4 v[108:111], v[20:21], off
	global_load_dwordx4 v[116:119], v[10:11], off
	global_load_dwordx4 v[120:123], v[40:41], off offset:256
	global_load_dwordx4 v[112:115], v[18:19], off
	global_load_dwordx4 v[124:127], v[12:13], off offset:256
	v_lshlrev_b32_e32 v46, 16, v0
	v_and_b32_e32 v47, 0xffff0000, v0
	v_lshlrev_b32_e32 v0, 16, v1
	v_and_b32_e32 v1, 0xffff0000, v1
	v_pk_mul_f32 v[30:31], v[30:31], s[48:49] op_sel_hi:[1,0]
	v_pk_add_f32 v[32:33], v[48:49], v[32:33] neg_lo:[0,1] neg_hi:[0,1]
	v_pk_mul_f32 v[0:1], v[0:1], s[48:49] op_sel_hi:[1,0]
	v_lshlrev_b32_e32 v48, 16, v2
	v_and_b32_e32 v49, 0xffff0000, v2
	v_lshlrev_b32_e32 v2, 16, v3
	v_and_b32_e32 v3, 0xffff0000, v3
	v_pk_mul_f32 v[2:3], v[2:3], s[48:49] op_sel_hi:[1,0]
	v_cvt_pk_bf16_f32 v89, v0, v1
	v_pk_mul_f32 v[0:1], v[30:31], v[24:25] op_sel:[0,1] op_sel_hi:[1,0]
	v_cvt_pk_bf16_f32 v91, v2, v3
	v_mov_b32_e32 v2, v28
	v_mov_b32_e32 v3, v0
	v_mov_b32_e32 v0, v29
	v_pk_add_f32 v[0:1], v[2:3], v[0:1] neg_lo:[0,1] neg_hi:[0,1]
	v_pk_mul_f32 v[2:3], v[30:31], v[24:25]
	v_mul_lo_u32 v10, v45, s97
	v_mov_b32_e32 v24, v26
	v_mov_b32_e32 v25, v2
	v_mov_b32_e32 v2, v27
	v_add_u32_e32 v10, 0, v10
	v_lshlrev_b32_e32 v4, 4, v4
	v_pk_add_f32 v[2:3], v[24:25], v[2:3]
	v_add_u32_e32 v176, v10, v4
	v_mul_lo_u32 v4, v5, s97
	v_cvt_pk_bf16_f32 v103, v2, v3
	v_mad_i64_i32 v[2:3], s[26:27], v5, s17, 0
	v_add_u32_e32 v4, 0, v4
	v_lshlrev_b32_e32 v5, 4, v6
	v_cvt_pk_bf16_f32 v96, v16, v17
	v_cvt_pk_bf16_f32 v99, v0, v1
	v_mad_i64_i32 v[0:1], s[26:27], v45, s17, 0
	v_mad_i64_i32 v[16:17], s[26:27], v7, s17, 0
	v_add_u32_e32 v177, v4, v5
	v_mul_lo_u32 v4, v7, s97
	v_add_u32_e32 v4, 0, v4
	v_lshlrev_b32_e32 v5, 4, v8
	s_movk_i32 s26, 0x108
	v_add_u32_e32 v178, v4, v5
	v_mul_lo_u32 v4, v9, s26
	v_add_u32_e32 v5, 0, v4
	s_movk_i32 s27, 0x6800
	v_add3_u32 v179, v5, v42, s27
	v_mul_lo_u32 v5, v50, s26
	v_add_u32_e32 v6, 0, v5
	v_add3_u32 v180, v6, v42, s27
	v_or_b32_e32 v181, 32, v161
	v_or_b32_e32 v182, 64, v161
	v_or_b32_e32 v183, 0x60, v161
	v_readlane_b32 s27, v254, 35
	v_mul_u32_u24_e32 v19, 0x108, v44
	v_mad_u32_u24 v18, v44, s97, 0
	v_add_u32_e32 v21, s27, v4
	v_add_u32_e32 v22, s27, v5
	v_add_u32_e32 v23, s27, v161
	v_add_u32_e32 v24, s27, v181
	v_mov_b32_e32 v4, s27
	v_add_u32_e32 v25, s27, v182
	v_add_u32_e32 v26, s27, v183
	v_readlane_b32 s27, v254, 36
	v_mad_u32_u24 v184, v44, s26, v4
	v_add_u32_e32 v20, 0, v161
	v_mov_b32_e32 v4, s27
	v_mad_u32_u24 v185, v44, s26, v4
	s_add_u32 s26, s15, 0x1a49c300
	v_add_u32_e32 v27, s27, v161
	v_add_u32_e32 v28, s27, v181
	v_add_u32_e32 v29, s27, v182
	v_add_u32_e32 v30, s27, v183
	s_addc_u32 s27, s5, 0
	v_mov_b64_e32 v[4:5], s[26:27]
	v_mad_i64_i32 v[166:167], s[26:27], v9, s16, v[4:5]
	v_mad_i64_i32 v[168:169], s[26:27], v50, s16, v[4:5]
	v_mad_i64_i32 v[4:5], s[26:27], s4, v231, v[16:17]
	v_mad_i64_i32 v[2:3], s[26:27], s4, v231, v[2:3]
	v_mad_i64_i32 v[0:1], s[4:5], s4, v231, v[0:1]
	v_lshl_add_u64 v[174:175], v[0:1], 0, v[14:15]
	v_mov_b32_e32 v14, v221
	v_mov_b32_e32 v15, v221
	v_add_u32_e32 v186, v21, v42
	v_add_u32_e32 v187, v22, v42
	v_add_u32_e32 v188, v23, v19
	v_add_u32_e32 v16, v24, v19
	v_add_u32_e32 v17, v25, v19
	v_add_u32_e32 v21, v26, v19
	v_add_u32_e32 v22, v28, v19
	v_add_u32_e32 v23, v29, v19
	v_add_u32_e32 v24, v30, v19
	v_pk_mul_f32 v[46:47], v[46:47], s[48:49] op_sel_hi:[1,0]
	v_pk_mul_f32 v[48:49], v[48:49], s[48:49] op_sel_hi:[1,0]
	v_lshl_add_u64 v[170:171], v[4:5], 0, v[36:37]
	v_lshl_add_u64 v[172:173], v[2:3], 0, v[38:39]
	v_mov_b32_e32 v0, v221
	v_mov_b32_e32 v1, v221
	v_mov_b32_e32 v2, v221
	v_mov_b32_e32 v3, v221
	v_mov_b32_e32 v4, v221
	v_mov_b32_e32 v5, v221
	v_mov_b32_e32 v6, v221
	v_mov_b32_e32 v7, v221
	v_mov_b32_e32 v8, v221
	v_mov_b32_e32 v9, v221
	v_mov_b32_e32 v10, v221
	v_mov_b32_e32 v11, v221
	v_mov_b32_e32 v12, v221
	v_mov_b32_e32 v13, v221
	v_add_u32_e32 v189, v27, v19
	v_add_u32_e32 v190, v18, v220
	v_add_u32_e32 v191, v20, v19
	v_add_u32_e32 v194, 0x2000, v16
	v_add_u32_e32 v204, 0x2000, v17
	v_add_u32_e32 v206, 0x2000, v21
	v_add_u32_e32 v208, 0x2000, v22
	v_add_u32_e32 v210, 0x2000, v23
	v_add_u32_e32 v211, 0x2000, v24
	v_mov_b64_e32 v[30:31], v[14:15]
	v_cvt_pk_bf16_f32 v88, v46, v47
	v_cvt_pk_bf16_f32 v90, v48, v49
	v_cvt_pk_bf16_f32 v97, v32, v33
	v_cvt_pk_bf16_f32 v101, v34, v35
	v_or_b32_e32 v166, v166, v42
	v_or_b32_e32 v168, v168, v42
	s_mov_b32 s4, 0
	v_mov_b32_e32 v212, 0xf149f2ca
	v_mov_b32_e32 v213, 0
	v_mov_b64_e32 v[28:29], v[12:13]
	v_mov_b64_e32 v[26:27], v[10:11]
	v_mov_b64_e32 v[24:25], v[8:9]
	v_mov_b64_e32 v[22:23], v[6:7]
	v_mov_b64_e32 v[20:21], v[4:5]
	v_mov_b64_e32 v[18:19], v[2:3]
	v_mov_b64_e32 v[16:17], v[0:1]
	v_and_b32_e32 v200, 15, v192
	v_lshrrev_b32_e32 v201, 4, v192
	v_mul_u32_u24_e32 v179, 0x110, v201
	v_lshrrev_b32_e32 v202, 1, v200
	v_lshl_add_u32 v179, v202, 5, v179
	v_and_b32_e32 v202, 1, v200
	v_lshl_add_u32 v179, v202, 3, v179
	v_add_u32_e32 v179, 0x6800, v179
	v_add_u32_e32 v180, 0x2200, v179
	v_add_u32_e32 v186, 0xac00, v179
	v_add_u32_e32 v187, 0xac00, v180
	v_and_b32_e32 v200, 31, v192
	v_bfe_u32 v201, v192, 5, 1
	v_mul_u32_u24_e32 v191, 0x110, v200
	v_lshl_add_u32 v191, v201, 4, v191
	v_add_u32_e32 v191, 0x6800, v191
	s_waitcnt vmcnt(9)
; DI void phase_attn(const Params& p, int hf, bool skipctx, char* smem, int& rot) {
;     ...
;     ATT_WRITE(ak0, ak1, ak2, av0, av1, 0);
;     __syncthreads();
	ds_write_b128 v176, v[76:79]
	s_waitcnt vmcnt(8)
	ds_write_b128 v177, v[80:83]
	s_waitcnt vmcnt(7)
	ds_write_b128 v178, v[84:87]
	s_waitcnt vmcnt(6)
	ds_write_b64 v179, v[92:93] offset:0
	ds_write_b64 v179, v[94:95] offset:16
	s_waitcnt vmcnt(5)
	ds_write_b64 v179, v[104:105] offset:8704
	ds_write_b64 v179, v[106:107] offset:8720
	s_waitcnt lgkmcnt(0)
	s_barrier
	v_mov_b32_e32 v194, v176
	v_mov_b32_e32 v204, v177
	v_mov_b32_e32 v206, v178
	v_mov_b32_e32 v208, v179
	v_mov_b32_e32 v210, v190
	v_mov_b32_e32 v211, v191
	v_mov_b32_e32 v220, 0xf149f2ca
	v_mov_b32_e32 v176, 0
	v_mov_b32_e32 v177, 0
	v_mov_b32_e32 v178, 0
	v_mov_b32_e32 v179, 0
	v_mov_b32_e32 v180, 0
	v_mov_b32_e32 v181, 0
	v_mov_b32_e32 v182, 0
	v_mov_b32_e32 v183, 0
	v_mov_b32_e32 v184, 0
	v_mov_b32_e32 v185, 0
	v_mov_b32_e32 v186, 0
	v_mov_b32_e32 v187, 0
	v_mov_b32_e32 v188, 0
	v_mov_b32_e32 v189, 0
	v_mov_b32_e32 v190, 0
	v_mov_b32_e32 v191, 0
